# v9 plus in-loop L2 lookahead loads (3 K-steps ahead of the DMA) in the projection K loops
# baseline (speedup 1.0000x reference)
.Lpf_skip_L0:
	s_sub_u32 s4, s4, s81
	s_subb_u32 s5, s5, 0
	s_sub_u32 s0, s0, s81
	s_subb_u32 s1, s1, 0
	s_add_u32 s27, s0, 0xc000
	s_addc_u32 s28, s1, 0
	s_add_u32 s29, s0, 0x8000
	s_addc_u32 s30, s1, 0
	s_add_u32 s31, s0, 0x4000
	s_addc_u32 s34, s1, 0
	s_add_u32 s35, s0, 0x0
	s_addc_u32 s36, s1, 0
	s_add_u32 s37, s4, 0xc000
	s_addc_u32 s39, s5, 0
	s_add_u32 s40, s4, 0x8000
	s_addc_u32 s42, s5, 0
	s_add_u32 s43, s4, 0x4000
	s_addc_u32 s44, s5, 0
	s_add_u32 s45, s4, 0x0
	s_addc_u32 s46, s5, 0
	s_mov_b64 s[0:1], 0
	s_mov_b32 s48, s17
	s_mov_b32 s47, s17
	v_mov_b32_e32 v0, v147
	v_mov_b32_e32 v1, v147
	v_mov_b32_e32 v2, v147
	v_mov_b32_e32 v3, v147
	v_mov_b32_e32 v4, v147
	v_mov_b32_e32 v5, v147
	v_mov_b32_e32 v6, v147
	v_mov_b32_e32 v7, v147
	v_mov_b32_e32 v8, v147
	v_mov_b32_e32 v9, v147
	v_mov_b32_e32 v10, v147
	v_mov_b32_e32 v11, v147
	v_mov_b32_e32 v12, v147
	v_mov_b32_e32 v13, v147
	v_mov_b32_e32 v14, v147
	v_mov_b32_e32 v15, v147
	v_mov_b32_e32 v16, v147
	v_mov_b32_e32 v17, v147
	v_mov_b32_e32 v18, v147
	v_mov_b32_e32 v19, v147
	v_mov_b32_e32 v20, v147
	v_mov_b32_e32 v21, v147
	v_mov_b32_e32 v22, v147
	v_mov_b32_e32 v23, v147
	v_mov_b32_e32 v24, v147
	v_mov_b32_e32 v25, v147
	v_mov_b32_e32 v26, v147
	v_mov_b32_e32 v27, v147
	v_mov_b32_e32 v28, v147
	v_mov_b32_e32 v29, v147
	v_mov_b32_e32 v30, v147
	v_mov_b32_e32 v31, v147
	v_mov_b32_e32 v32, v147
	v_mov_b32_e32 v33, v147
	v_mov_b32_e32 v34, v147
	v_mov_b32_e32 v35, v147
	v_mov_b32_e32 v36, v147
	v_mov_b32_e32 v37, v147
	v_mov_b32_e32 v38, v147
	v_mov_b32_e32 v39, v147
	v_mov_b32_e32 v40, v147
	v_mov_b32_e32 v41, v147
	v_mov_b32_e32 v42, v147
	v_mov_b32_e32 v43, v147
	v_mov_b32_e32 v44, v147
	v_mov_b32_e32 v45, v147
	v_mov_b32_e32 v46, v147
	v_mov_b32_e32 v47, v147
	v_mov_b32_e32 v48, v147
	v_mov_b32_e32 v49, v147
	v_mov_b32_e32 v50, v147
	v_mov_b32_e32 v51, v147
	v_mov_b32_e32 v52, v147
	v_mov_b32_e32 v53, v147
	v_mov_b32_e32 v54, v147
	v_mov_b32_e32 v55, v147
	v_mov_b32_e32 v56, v147
	v_mov_b32_e32 v57, v147
	v_mov_b32_e32 v58, v147
	v_mov_b32_e32 v59, v147
	v_mov_b32_e32 v60, v147
	v_mov_b32_e32 v61, v147
	v_mov_b32_e32 v62, v147
	v_mov_b32_e32 v63, v147
	v_mov_b32_e32 v64, v147
	v_mov_b32_e32 v65, v147
	v_mov_b32_e32 v66, v147
	v_mov_b32_e32 v67, v147
	v_mov_b32_e32 v68, v147
	v_mov_b32_e32 v69, v147
	v_mov_b32_e32 v70, v147
	v_mov_b32_e32 v71, v147
	v_mov_b32_e32 v72, v147
	v_mov_b32_e32 v73, v147
	v_mov_b32_e32 v74, v147
	v_mov_b32_e32 v75, v147
	v_mov_b32_e32 v76, v147
	v_mov_b32_e32 v77, v147
	v_mov_b32_e32 v78, v147
	v_mov_b32_e32 v79, v147
	v_mov_b32_e32 v80, v147
	v_mov_b32_e32 v81, v147
	v_mov_b32_e32 v82, v147
	v_mov_b32_e32 v83, v147
	v_mov_b32_e32 v84, v147
	v_mov_b32_e32 v85, v147
	v_mov_b32_e32 v86, v147
	v_mov_b32_e32 v87, v147
	v_mov_b32_e32 v88, v147
	v_mov_b32_e32 v89, v147
	v_mov_b32_e32 v90, v147
	v_mov_b32_e32 v91, v147
	v_mov_b32_e32 v92, v147
	v_mov_b32_e32 v93, v147
	v_mov_b32_e32 v94, v147
	v_mov_b32_e32 v95, v147
	v_mov_b32_e32 v96, v147
	v_mov_b32_e32 v97, v147
	v_mov_b32_e32 v98, v147
	v_mov_b32_e32 v99, v147
	v_mov_b32_e32 v100, v147
	v_mov_b32_e32 v101, v147
	v_mov_b32_e32 v102, v147
	v_mov_b32_e32 v103, v147
	v_mov_b32_e32 v104, v147
	v_mov_b32_e32 v105, v147
	v_mov_b32_e32 v106, v147
	v_mov_b32_e32 v107, v147
	v_mov_b32_e32 v108, v147
	v_mov_b32_e32 v109, v147
	v_mov_b32_e32 v110, v147
	v_mov_b32_e32 v111, v147
	v_mov_b32_e32 v112, v147
	v_mov_b32_e32 v113, v147
	v_mov_b32_e32 v114, v147
	v_mov_b32_e32 v115, v147
	v_mov_b32_e32 v116, v147
	v_mov_b32_e32 v117, v147
	v_mov_b32_e32 v118, v147
	v_mov_b32_e32 v119, v147
	v_mov_b32_e32 v120, v147
	v_mov_b32_e32 v121, v147
	v_mov_b32_e32 v122, v147
	v_mov_b32_e32 v123, v147
	v_mov_b32_e32 v124, v147
	v_mov_b32_e32 v125, v147
	v_mov_b32_e32 v126, v147
	v_mov_b32_e32 v127, v147
	s_sub_u32 s76, s45, s35
	v_lshrrev_b32_e32 v196, 5, v179
	v_add_u32_e32 v196, -1, v196
	v_and_b32_e32 v196, s76, v196
	v_and_b32_e32 v194, 31, v179
	v_lshl_add_u32 v194, v194, 11, v196
	s_cmp_eq_u32 s80, 1
	s_cbranch_scc0 .Lpfp_L0
	s_mov_b32 s80, 0
	s_waitcnt vmcnt(16)
	s_barrier
	s_branch .Lkin_L0
.Lpfp_L0:
	s_add_u32 s76, s81, 0x80
	s_and_b32 s76, s76, 0x7ff
	s_add_u32 s78, s35, s76
	s_addc_u32 s79, s36, 0
	global_load_dword v195, v194, s[78:79]
	s_add_u32 s76, s81, 0x100
	s_and_b32 s76, s76, 0x7ff
	s_add_u32 s78, s35, s76
	s_addc_u32 s79, s36, 0
	global_load_dword v195, v194, s[78:79]
	s_add_u32 s76, s81, 0x180
	s_and_b32 s76, s76, 0x7ff
	s_add_u32 s78, s35, s76
	s_addc_u32 s79, s36, 0
	global_load_dword v195, v194, s[78:79]
	s_add_u32 s76, s81, 0x200
	s_and_b32 s76, s76, 0x7ff
	s_add_u32 s78, s35, s76
	s_addc_u32 s79, s36, 0
	global_load_dword v195, v194, s[78:79]
	s_branch .LBB0_131

.LBB0_131:
	s_waitcnt vmcnt(1)
	s_barrier

.LBB0_133:
	s_andn2_b64 vcc, exec, s[4:5]
	s_cbranch_vccnz .LBB0_130
	s_add_i32 s52, s48, 0x10000
	s_and_b32 s4, s52, 0x10000
	s_add_i32 s53, s4, s26
	s_add_i32 s54, s53, 0x8000
	s_add_u32 s82, s0, s81
	s_addk_i32 s82, 0x80
	s_and_b32 s82, s82, 0x7ff
	s_mov_b32 s83, 0
	s_add_u32 s4, s45, s82
	s_addc_u32 s5, s46, s83
	s_mov_b32 m0, s53
	global_load_lds_dwordx4 v145, s[4:5]
	s_add_u32 s4, s43, s82
	s_addc_u32 s5, s44, s83
	s_add_i32 s55, s53, 0x400
	s_mov_b32 m0, s55
	global_load_lds_dwordx4 v185, s[4:5]
	s_add_u32 s4, s40, s82
	s_addc_u32 s5, s42, s83
	s_add_i32 s55, s53, 0x800
	s_mov_b32 m0, s55
	global_load_lds_dwordx4 v145, s[4:5]
	s_add_u32 s4, s37, s82
	s_addc_u32 s5, s39, s83
	s_add_i32 s55, s53, 0xc00
	s_mov_b32 m0, s55
	global_load_lds_dwordx4 v185, s[4:5]
	s_add_u32 s4, s35, s82
	s_addc_u32 s5, s36, s83
	s_mov_b32 m0, s54
	global_load_lds_dwordx4 v145, s[4:5]
	s_add_u32 s4, s31, s82
	s_addc_u32 s5, s34, s83
	s_add_i32 s54, s53, 0x8400
	s_mov_b32 m0, s54
	global_load_lds_dwordx4 v185, s[4:5]
	s_add_u32 s4, s29, s82
	s_addc_u32 s5, s30, s83
	s_add_i32 s54, s53, 0x8800
	s_mov_b32 m0, s54
	global_load_lds_dwordx4 v145, s[4:5]
	s_add_u32 s4, s27, s82
	s_addc_u32 s5, s28, s83
	s_add_i32 s53, s53, 0x8c00
	s_mov_b32 m0, s53
	global_load_lds_dwordx4 v185, s[4:5]
	s_add_u32 s76, s0, s81
	s_addk_i32 s76, 0x200
	s_and_b32 s76, s76, 0x7ff
	s_add_u32 s78, s35, s76
	s_addc_u32 s79, s36, 0
	global_load_dword v195, v194, s[78:79]
	s_branch .LBB0_130

.Lpe_notv_L0:
	s_cmp_ge_u32 s25, 9
	s_cbranch_scc1 .Lpe_gates_L0
	s_lshr_b32 s34, s25, 1
	s_cmp_ge_u32 s25, 6
	s_cselect_b32 s35, 1, 0
	s_sub_u32 s34, s34, s35
	s_lshl_b32 s35, s98, 2
	s_add_u32 s35, s35, s34
	s_lshl_b32 s35, s35, 8
	v_readlane_b32 s82, v254, 14
	v_readlane_b32 s83, v254, 15
	s_add_u32 s82, s82, s35
	s_addc_u32 s83, s83, 0
	global_load_dwordx4 v[198:201], v146, s[82:83] offset:0
	global_load_dwordx4 v[202:205], v146, s[82:83] offset:32
	global_load_dwordx4 v[206:209], v146, s[82:83] offset:64
	global_load_dwordx4 v[210:213], v146, s[82:83] offset:96
	global_load_dwordx4 v[214:217], v146, s[82:83] offset:128
	global_load_dwordx4 v[218:221], v146, s[82:83] offset:160
	global_load_dwordx4 v[222:225], v146, s[82:83] offset:192
	global_load_dwordx4 v[226:229], v146, s[82:83] offset:224
	s_and_b32 s35, s34, 1
	s_cmp_eq_u32 s35, 0
	s_cselect_b32 s36, 0x3e000000, 1.0
	s_and_b32 s35, s29, 0x7ff
	s_lshl_b32 s35, s35, 7
	s_add_u32 s96, s72, 0x1ada0000
	s_addc_u32 s97, s73, 0
	s_add_u32 s96, s96, s35
	s_addc_u32 s97, s97, 0
	s_add_u32 s100, s96, 0x40000
	s_addc_u32 s101, s97, 0
	s_cmp_ge_u32 s34, 2
	s_cselect_b32 s37, 1, 0
	s_waitcnt vmcnt(8)
	v_lshlrev_b32_e32 v180, 7, v197
	v_add_u32_e32 v180, v180, v146
	v_mov_b32_e32 v197, 0x358637bd
	v_pk_add_f32 v[128:129], v[128:129], v[130:131]
	v_pk_add_f32 v[132:133], v[132:133], v[134:135]
	v_pk_add_f32 v[136:137], v[136:137], v[138:139]
	v_pk_add_f32 v[140:141], v[140:141], v[142:143]
	v_pk_add_f32 v[164:165], v[164:165], v[166:167]
	v_pk_add_f32 v[168:169], v[168:169], v[170:171]
	v_pk_add_f32 v[246:247], v[246:247], v[248:249]
	v_pk_add_f32 v[250:251], v[250:251], v[252:253]
	v_pk_add_f32 v[128:129], v[128:129], v[132:133]
	v_pk_add_f32 v[136:137], v[136:137], v[140:141]
	v_pk_add_f32 v[164:165], v[164:165], v[168:169]
	v_pk_add_f32 v[246:247], v[246:247], v[250:251]
	v_add_f32_e32 v128, v128, v129
	v_add_f32_e32 v136, v136, v137
	v_add_f32_e32 v164, v164, v165
	v_add_f32_e32 v246, v246, v247
	v_fmamk_f32 v128, v128, 0x3a800000, v197
	v_fmamk_f32 v136, v136, 0x3a800000, v197
	v_fmamk_f32 v164, v164, 0x3a800000, v197
	v_fmamk_f32 v246, v246, 0x3a800000, v197
	v_rsq_f32_e32 v172, v128
	v_rsq_f32_e32 v173, v136
	v_rsq_f32_e32 v174, v164
	v_rsq_f32_e32 v175, v246
	s_nop 0
	s_add_u32 s76, s99, s90
	s_cmp_lt_u32 s76, 0x440
	s_cselect_b32 s80, 1, 0
	s_cselect_b32 s83, 0x200000, 0
	s_lshl_b32 s76, s24, 19
	s_lshl_b32 s77, s26, 16
	s_add_u32 s76, s76, s77
	s_and_b32 s77, s24, 7
	s_lshl_b32 s77, s77, 8
	s_add_u32 s76, s76, s77
	s_add_u32 s78, s72, 0xa120000
	s_addc_u32 s79, s73, 0
	s_add_u32 s78, s78, s76
	s_addc_u32 s79, s79, 0
	s_lshl_b32 s76, s25, 19
	s_add_u32 s76, s76, s83
	s_add_u32 s76, s76, s77
	s_lshl_b32 s77, s26, 16
	s_add_u32 s76, s76, s77
	s_add_u32 s82, s72, 0x0
	s_addc_u32 s83, s73, 0
	s_add_u32 s82, s82, s76
	s_addc_u32 s83, s83, 0
	s_lshl_b32 s76, s26, 12
	s_mov_b32 m0, s76
	s_nop 0
	global_load_lds_dwordx4 v145, s[78:79]
	s_add_u32 s78, s78, 0x4000
	s_addc_u32 s79, s79, 0
	s_add_u32 s76, s76, 0x400
	s_mov_b32 m0, s76
	s_nop 0
	global_load_lds_dwordx4 v185, s[78:79]
	s_add_u32 s78, s78, 0x4000
	s_addc_u32 s79, s79, 0
	s_add_u32 s76, s76, 0x400
	s_mov_b32 m0, s76
	s_nop 0
	global_load_lds_dwordx4 v145, s[78:79]
	s_add_u32 s78, s78, 0x4000
	s_addc_u32 s79, s79, 0
	s_add_u32 s76, s76, 0x400
	s_mov_b32 m0, s76
	s_nop 0
	global_load_lds_dwordx4 v185, s[78:79]
	s_add_u32 s78, s78, 0x4000
	s_addc_u32 s79, s79, 0
	s_add_u32 s76, s76, 0x400
	s_add_u32 s76, s76, 0x7000
	s_mov_b32 m0, s76
	s_nop 0
	global_load_lds_dwordx4 v145, s[82:83]
	s_add_u32 s82, s82, 0x4000
	s_addc_u32 s83, s83, 0
	s_add_u32 s76, s76, 0x400
	s_mov_b32 m0, s76
	s_nop 0
	global_load_lds_dwordx4 v185, s[82:83]
	s_add_u32 s82, s82, 0x4000
	s_addc_u32 s83, s83, 0
	s_add_u32 s76, s76, 0x400
	s_mov_b32 m0, s76
	s_nop 0
	global_load_lds_dwordx4 v145, s[82:83]
	s_add_u32 s82, s82, 0x4000
	s_addc_u32 s83, s83, 0
	s_add_u32 s76, s76, 0x400
	s_mov_b32 m0, s76
	s_nop 0
	global_load_lds_dwordx4 v185, s[82:83]
	s_add_u32 s82, s82, 0x4000
	s_addc_u32 s83, s83, 0
	s_add_u32 s76, s76, 0x400
	s_and_b32 s77, s24, 7
	s_lshl_b32 s77, s77, 8
	s_add_u32 s76, s77, 0x10000
	s_sub_u32 s78, s78, s76
	s_subb_u32 s79, s79, 0
	s_sub_u32 s82, s82, s76
	s_subb_u32 s83, s83, 0
	s_sub_u32 s76, s78, s82
	v_lshrrev_b32_e32 v196, 5, v179
	v_add_u32_e32 v196, -1, v196
	v_and_b32_e32 v196, s76, v196
	v_and_b32_e32 v194, 31, v179
	v_lshl_add_u32 v194, v194, 11, v196
	s_add_u32 s76, s77, 0x80
	s_and_b32 s76, s76, 0x7ff
	s_add_u32 s78, s82, s76
	s_addc_u32 s79, s83, 0
	global_load_dword v195, v194, s[78:79]
	s_add_u32 s76, s77, 0x100
	s_and_b32 s76, s76, 0x7ff
	s_add_u32 s78, s82, s76
	s_addc_u32 s79, s83, 0
	global_load_dword v195, v194, s[78:79]
	s_add_u32 s76, s77, 0x180
	s_and_b32 s76, s76, 0x7ff
	s_add_u32 s78, s82, s76
	s_addc_u32 s79, s83, 0
	global_load_dword v195, v194, s[78:79]
	s_add_u32 s76, s77, 0x200
	s_and_b32 s76, s76, 0x7ff
	s_add_u32 s78, s82, s76
	s_addc_u32 s79, s83, 0
	global_load_dword v195, v194, s[78:79]
	s_cmp_eq_u32 s37, 0
	s_cbranch_scc1 .Lpe_norope_ld_L0
	global_load_dwordx4 v[230:233], v180, s[96:97] offset:0
	global_load_dwordx4 v[234:237], v180, s[96:97] offset:32
	global_load_dwordx4 v[238:241], v180, s[96:97] offset:64
	global_load_dwordx4 v[242:245], v180, s[96:97] offset:96
	global_load_dwordx4 v[148:151], v180, s[100:101] offset:0
	global_load_dwordx4 v[152:155], v180, s[100:101] offset:32
	global_load_dwordx4 v[156:159], v180, s[100:101] offset:64
	global_load_dwordx4 v[160:163], v180, s[100:101] offset:96
.Lpe_norope_ld_L0:
	v_pk_mul_f32 v[128:129], v[0:1], v[0:1]
	v_pk_mul_f32 v[130:131], v[16:17], v[16:17]
	v_pk_mul_f32 v[132:133], v[32:33], v[32:33]
	v_pk_mul_f32 v[134:135], v[48:49], v[48:49]
	v_pk_mul_f32 v[136:137], v[64:65], v[64:65]
	v_pk_mul_f32 v[138:139], v[80:81], v[80:81]
	v_pk_mul_f32 v[140:141], v[96:97], v[96:97]
	v_pk_mul_f32 v[142:143], v[112:113], v[112:113]
	v_pk_fma_f32 v[128:129], v[2:3], v[2:3], v[128:129]
	v_pk_fma_f32 v[130:131], v[18:19], v[18:19], v[130:131]
	v_pk_fma_f32 v[132:133], v[34:35], v[34:35], v[132:133]
	v_pk_fma_f32 v[134:135], v[50:51], v[50:51], v[134:135]
	v_pk_fma_f32 v[136:137], v[66:67], v[66:67], v[136:137]
	v_pk_fma_f32 v[138:139], v[82:83], v[82:83], v[138:139]
	v_pk_fma_f32 v[140:141], v[98:99], v[98:99], v[140:141]
	v_pk_fma_f32 v[142:143], v[114:115], v[114:115], v[142:143]
	v_pk_fma_f32 v[128:129], v[4:5], v[4:5], v[128:129]
	v_pk_fma_f32 v[130:131], v[20:21], v[20:21], v[130:131]
	v_pk_fma_f32 v[132:133], v[36:37], v[36:37], v[132:133]
	v_pk_fma_f32 v[134:135], v[52:53], v[52:53], v[134:135]
	v_pk_fma_f32 v[136:137], v[68:69], v[68:69], v[136:137]
	v_pk_fma_f32 v[138:139], v[84:85], v[84:85], v[138:139]
	v_pk_fma_f32 v[140:141], v[100:101], v[100:101], v[140:141]
	v_pk_fma_f32 v[142:143], v[116:117], v[116:117], v[142:143]
	v_pk_fma_f32 v[128:129], v[6:7], v[6:7], v[128:129]
	v_pk_fma_f32 v[130:131], v[22:23], v[22:23], v[130:131]
	v_pk_fma_f32 v[132:133], v[38:39], v[38:39], v[132:133]
	v_pk_fma_f32 v[134:135], v[54:55], v[54:55], v[134:135]
	v_pk_fma_f32 v[136:137], v[70:71], v[70:71], v[136:137]
	v_pk_fma_f32 v[138:139], v[86:87], v[86:87], v[138:139]
	v_pk_fma_f32 v[140:141], v[102:103], v[102:103], v[140:141]
	v_pk_fma_f32 v[142:143], v[118:119], v[118:119], v[142:143]
	v_pk_fma_f32 v[128:129], v[8:9], v[8:9], v[128:129]
	v_pk_fma_f32 v[130:131], v[24:25], v[24:25], v[130:131]
	v_pk_fma_f32 v[132:133], v[40:41], v[40:41], v[132:133]
	v_pk_fma_f32 v[134:135], v[56:57], v[56:57], v[134:135]
	v_pk_fma_f32 v[136:137], v[72:73], v[72:73], v[136:137]
	v_pk_fma_f32 v[138:139], v[88:89], v[88:89], v[138:139]
	v_pk_fma_f32 v[140:141], v[104:105], v[104:105], v[140:141]
	v_pk_fma_f32 v[142:143], v[120:121], v[120:121], v[142:143]
	v_pk_fma_f32 v[128:129], v[10:11], v[10:11], v[128:129]
	v_pk_fma_f32 v[130:131], v[26:27], v[26:27], v[130:131]
	v_pk_fma_f32 v[132:133], v[42:43], v[42:43], v[132:133]
	v_pk_fma_f32 v[134:135], v[58:59], v[58:59], v[134:135]
	v_pk_fma_f32 v[136:137], v[74:75], v[74:75], v[136:137]
	v_pk_fma_f32 v[138:139], v[90:91], v[90:91], v[138:139]
	v_pk_fma_f32 v[140:141], v[106:107], v[106:107], v[140:141]
	v_pk_fma_f32 v[142:143], v[122:123], v[122:123], v[142:143]
	v_pk_fma_f32 v[128:129], v[12:13], v[12:13], v[128:129]
	v_pk_fma_f32 v[130:131], v[28:29], v[28:29], v[130:131]
	v_pk_fma_f32 v[132:133], v[44:45], v[44:45], v[132:133]
	v_pk_fma_f32 v[134:135], v[60:61], v[60:61], v[134:135]
	v_pk_fma_f32 v[136:137], v[76:77], v[76:77], v[136:137]
	v_pk_fma_f32 v[138:139], v[92:93], v[92:93], v[138:139]
	v_pk_fma_f32 v[140:141], v[108:109], v[108:109], v[140:141]
	v_pk_fma_f32 v[142:143], v[124:125], v[124:125], v[142:143]
	v_pk_fma_f32 v[128:129], v[14:15], v[14:15], v[128:129]
	v_pk_fma_f32 v[130:131], v[30:31], v[30:31], v[130:131]
	v_pk_fma_f32 v[132:133], v[46:47], v[46:47], v[132:133]
	v_pk_fma_f32 v[134:135], v[62:63], v[62:63], v[134:135]
	v_pk_fma_f32 v[136:137], v[78:79], v[78:79], v[136:137]
	v_pk_fma_f32 v[138:139], v[94:95], v[94:95], v[138:139]
	v_pk_fma_f32 v[140:141], v[110:111], v[110:111], v[140:141]
	v_pk_fma_f32 v[142:143], v[126:127], v[126:127], v[142:143]
	v_pk_add_f32 v[128:129], v[128:129], v[130:131]
	v_pk_add_f32 v[132:133], v[132:133], v[134:135]
	v_pk_add_f32 v[136:137], v[136:137], v[138:139]
	v_pk_add_f32 v[140:141], v[140:141], v[142:143]
	v_add_f32_e32 v164, v128, v129
	v_add_f32_e32 v165, v132, v133
	v_add_f32_e32 v166, v136, v137
	v_add_f32_e32 v167, v140, v141
	v_mov_b32_e32 v168, v164
	v_mov_b32_e32 v169, v165
	v_mov_b32_e32 v170, v166
	v_mov_b32_e32 v171, v167
	s_nop 1
	v_permlane32_swap_b32_e32 v168, v164
	v_permlane32_swap_b32_e32 v169, v165
	v_permlane32_swap_b32_e32 v170, v166
	v_permlane32_swap_b32_e32 v171, v167
	v_add_f32_e32 v164, v164, v168
	v_add_f32_e32 v165, v165, v169
	v_add_f32_e32 v166, v166, v170
	v_add_f32_e32 v167, v167, v171
	v_mul_f32_e32 v168, v172, v172
	v_mul_f32_e32 v169, v173, v173
	v_mul_f32_e32 v170, v174, v174
	v_mul_f32_e32 v171, v175, v175
	v_mul_f32_e32 v168, v168, v164
	v_mul_f32_e32 v169, v169, v165
	v_mul_f32_e32 v170, v170, v166
	v_mul_f32_e32 v171, v171, v167
	v_fmamk_f32 v168, v168, 0x3c800000, v197
	v_fmamk_f32 v169, v169, 0x3c800000, v197
	v_fmamk_f32 v170, v170, 0x3c800000, v197
	v_fmamk_f32 v171, v171, 0x3c800000, v197
	v_rsq_f32_e32 v168, v168
	v_rsq_f32_e32 v169, v169
	v_rsq_f32_e32 v170, v170
	v_rsq_f32_e32 v171, v171
	s_nop 0
	v_mul_f32_e32 v172, v172, v168
	v_mul_f32_e32 v173, v173, v169
	v_mul_f32_e32 v174, v174, v170
	v_mul_f32_e32 v175, v175, v171
	v_mul_f32_e32 v172, s36, v172
	v_mul_f32_e32 v173, s36, v173
	v_mul_f32_e32 v174, s36, v174
	v_mul_f32_e32 v175, s36, v175
	v_pk_mul_f32 v[0:1], v[0:1], v[172:173] op_sel_hi:[1,0]
	v_pk_mul_f32 v[2:3], v[2:3], v[172:173] op_sel_hi:[1,0]
	v_pk_mul_f32 v[4:5], v[4:5], v[172:173] op_sel_hi:[1,0]
	v_pk_mul_f32 v[6:7], v[6:7], v[172:173] op_sel_hi:[1,0]
	v_pk_mul_f32 v[8:9], v[8:9], v[172:173] op_sel_hi:[1,0]
	v_pk_mul_f32 v[10:11], v[10:11], v[172:173] op_sel_hi:[1,0]
	v_pk_mul_f32 v[12:13], v[12:13], v[172:173] op_sel_hi:[1,0]
	v_pk_mul_f32 v[14:15], v[14:15], v[172:173] op_sel_hi:[1,0]
	v_pk_mul_f32 v[16:17], v[16:17], v[172:173] op_sel_hi:[1,0]
	v_pk_mul_f32 v[18:19], v[18:19], v[172:173] op_sel_hi:[1,0]
	v_pk_mul_f32 v[20:21], v[20:21], v[172:173] op_sel_hi:[1,0]
	v_pk_mul_f32 v[22:23], v[22:23], v[172:173] op_sel_hi:[1,0]
	v_pk_mul_f32 v[24:25], v[24:25], v[172:173] op_sel_hi:[1,0]
	v_pk_mul_f32 v[26:27], v[26:27], v[172:173] op_sel_hi:[1,0]
	v_pk_mul_f32 v[28:29], v[28:29], v[172:173] op_sel_hi:[1,0]
	v_pk_mul_f32 v[30:31], v[30:31], v[172:173] op_sel_hi:[1,0]
	s_cmp_eq_u32 s37, 0
	s_cbranch_scc1 .Lpe_wg_norope_L0
	s_waitcnt vmcnt(20)
	s_branch .Lpe_wg_done_L0
.Lpe_wg_norope_L0:
	s_waitcnt vmcnt(12)

.Lpe_gates_L0:
	s_lshl_b32 s35, s98, 11
	s_add_u32 s35, s35, s30
	s_sub_u32 s35, s35, 0x900
	s_lshl_b32 s35, s35, 2
	v_readlane_b32 s82, v254, 12
	v_readlane_b32 s83, v254, 13
	s_add_u32 s82, s82, s35
	s_addc_u32 s83, s83, 0
	global_load_dwordx4 v[198:201], v146, s[82:83] offset:0
	global_load_dwordx4 v[202:205], v146, s[82:83] offset:32
	global_load_dwordx4 v[206:209], v146, s[82:83] offset:64
	global_load_dwordx4 v[210:213], v146, s[82:83] offset:96
	global_load_dwordx4 v[214:217], v146, s[82:83] offset:128
	global_load_dwordx4 v[218:221], v146, s[82:83] offset:160
	global_load_dwordx4 v[222:225], v146, s[82:83] offset:192
	global_load_dwordx4 v[226:229], v146, s[82:83] offset:224
	s_waitcnt vmcnt(8)
	v_mov_b32_e32 v197, 0x358637bd
	v_pk_add_f32 v[128:129], v[128:129], v[130:131]
	v_pk_add_f32 v[132:133], v[132:133], v[134:135]
	v_pk_add_f32 v[136:137], v[136:137], v[138:139]
	v_pk_add_f32 v[140:141], v[140:141], v[142:143]
	v_pk_add_f32 v[164:165], v[164:165], v[166:167]
	v_pk_add_f32 v[168:169], v[168:169], v[170:171]
	v_pk_add_f32 v[246:247], v[246:247], v[248:249]
	v_pk_add_f32 v[250:251], v[250:251], v[252:253]
	v_pk_add_f32 v[128:129], v[128:129], v[132:133]
	v_pk_add_f32 v[136:137], v[136:137], v[140:141]
	v_pk_add_f32 v[164:165], v[164:165], v[168:169]
	v_pk_add_f32 v[246:247], v[246:247], v[250:251]
	v_add_f32_e32 v128, v128, v129
	v_add_f32_e32 v136, v136, v137
	v_add_f32_e32 v164, v164, v165
	v_add_f32_e32 v246, v246, v247
	v_fmamk_f32 v128, v128, 0x3a800000, v197
	v_fmamk_f32 v136, v136, 0x3a800000, v197
	v_fmamk_f32 v164, v164, 0x3a800000, v197
	v_fmamk_f32 v246, v246, 0x3a800000, v197
	v_rsq_f32_e32 v172, v128
	v_rsq_f32_e32 v173, v136
	v_rsq_f32_e32 v174, v164
	v_rsq_f32_e32 v175, v246
	s_nop 0
	s_add_u32 s76, s99, s90
	s_cmp_lt_u32 s76, 0x440
	s_cselect_b32 s80, 1, 0
	s_cselect_b32 s83, 0x200000, 0
	s_lshl_b32 s76, s24, 19
	s_lshl_b32 s77, s26, 16
	s_add_u32 s76, s76, s77
	s_and_b32 s77, s24, 7
	s_lshl_b32 s77, s77, 8
	s_add_u32 s76, s76, s77
	s_add_u32 s78, s72, 0xa120000
	s_addc_u32 s79, s73, 0
	s_add_u32 s78, s78, s76
	s_addc_u32 s79, s79, 0
	s_lshl_b32 s76, s25, 19
	s_add_u32 s76, s76, s83
	s_add_u32 s76, s76, s77
	s_lshl_b32 s77, s26, 16
	s_add_u32 s76, s76, s77
	s_add_u32 s82, s72, 0x0
	s_addc_u32 s83, s73, 0
	s_add_u32 s82, s82, s76
	s_addc_u32 s83, s83, 0
	s_lshl_b32 s76, s26, 12
	s_mov_b32 m0, s76
	s_nop 0
	global_load_lds_dwordx4 v145, s[78:79]
	s_add_u32 s78, s78, 0x4000
	s_addc_u32 s79, s79, 0
	s_add_u32 s76, s76, 0x400
	s_mov_b32 m0, s76
	s_nop 0
	global_load_lds_dwordx4 v185, s[78:79]
	s_add_u32 s78, s78, 0x4000
	s_addc_u32 s79, s79, 0
	s_add_u32 s76, s76, 0x400
	s_mov_b32 m0, s76
	s_nop 0
	global_load_lds_dwordx4 v145, s[78:79]
	s_add_u32 s78, s78, 0x4000
	s_addc_u32 s79, s79, 0
	s_add_u32 s76, s76, 0x400
	s_mov_b32 m0, s76
	s_nop 0
	global_load_lds_dwordx4 v185, s[78:79]
	s_add_u32 s78, s78, 0x4000
	s_addc_u32 s79, s79, 0
	s_add_u32 s76, s76, 0x400
	s_add_u32 s76, s76, 0x7000
	s_mov_b32 m0, s76
	s_nop 0
	global_load_lds_dwordx4 v145, s[82:83]
	s_add_u32 s82, s82, 0x4000
	s_addc_u32 s83, s83, 0
	s_add_u32 s76, s76, 0x400
	s_mov_b32 m0, s76
	s_nop 0
	global_load_lds_dwordx4 v185, s[82:83]
	s_add_u32 s82, s82, 0x4000
	s_addc_u32 s83, s83, 0
	s_add_u32 s76, s76, 0x400
	s_mov_b32 m0, s76
	s_nop 0
	global_load_lds_dwordx4 v145, s[82:83]
	s_add_u32 s82, s82, 0x4000
	s_addc_u32 s83, s83, 0
	s_add_u32 s76, s76, 0x400
	s_mov_b32 m0, s76
	s_nop 0
	global_load_lds_dwordx4 v185, s[82:83]
	s_add_u32 s82, s82, 0x4000
	s_addc_u32 s83, s83, 0
	s_add_u32 s76, s76, 0x400
	s_and_b32 s77, s24, 7
	s_lshl_b32 s77, s77, 8
	s_add_u32 s76, s77, 0x10000
	s_sub_u32 s78, s78, s76
	s_subb_u32 s79, s79, 0
	s_sub_u32 s82, s82, s76
	s_subb_u32 s83, s83, 0
	s_sub_u32 s76, s78, s82
	v_lshrrev_b32_e32 v196, 5, v179
	v_add_u32_e32 v196, -1, v196
	v_and_b32_e32 v196, s76, v196
	v_and_b32_e32 v194, 31, v179
	v_lshl_add_u32 v194, v194, 11, v196
	s_add_u32 s76, s77, 0x80
	s_and_b32 s76, s76, 0x7ff
	s_add_u32 s78, s82, s76
	s_addc_u32 s79, s83, 0
	global_load_dword v195, v194, s[78:79]
	s_add_u32 s76, s77, 0x100
	s_and_b32 s76, s76, 0x7ff
	s_add_u32 s78, s82, s76
	s_addc_u32 s79, s83, 0
	global_load_dword v195, v194, s[78:79]
	s_add_u32 s76, s77, 0x180
	s_and_b32 s76, s76, 0x7ff
	s_add_u32 s78, s82, s76
	s_addc_u32 s79, s83, 0
	global_load_dword v195, v194, s[78:79]
	s_add_u32 s76, s77, 0x200
	s_and_b32 s76, s76, 0x7ff
	s_add_u32 s78, s82, s76
	s_addc_u32 s79, s83, 0
	global_load_dword v195, v194, s[78:79]
	v_mul_f32_e32 v172, 0xbfb8aa3b, v172
	v_mul_f32_e32 v173, 0xbfb8aa3b, v173
	v_mul_f32_e32 v174, 0xbfb8aa3b, v174
	v_mul_f32_e32 v175, 0xbfb8aa3b, v175
	s_waitcnt vmcnt(12)
	v_mul_f32_e32 v198, 0xbfb8aa3b, v198
	v_mul_f32_e32 v199, 0xbfb8aa3b, v199
	v_mul_f32_e32 v200, 0xbfb8aa3b, v200
	v_mul_f32_e32 v201, 0xbfb8aa3b, v201
	v_mul_f32_e32 v202, 0xbfb8aa3b, v202
	v_mul_f32_e32 v203, 0xbfb8aa3b, v203
	v_mul_f32_e32 v204, 0xbfb8aa3b, v204
	v_mul_f32_e32 v205, 0xbfb8aa3b, v205
	v_mul_f32_e32 v206, 0xbfb8aa3b, v206
	v_mul_f32_e32 v207, 0xbfb8aa3b, v207
	v_mul_f32_e32 v208, 0xbfb8aa3b, v208
	v_mul_f32_e32 v209, 0xbfb8aa3b, v209
	v_mul_f32_e32 v210, 0xbfb8aa3b, v210
	v_mul_f32_e32 v211, 0xbfb8aa3b, v211
	v_mul_f32_e32 v212, 0xbfb8aa3b, v212
	v_mul_f32_e32 v213, 0xbfb8aa3b, v213
	v_mul_f32_e32 v214, 0xbfb8aa3b, v214
	v_mul_f32_e32 v215, 0xbfb8aa3b, v215
	v_mul_f32_e32 v216, 0xbfb8aa3b, v216
	v_mul_f32_e32 v217, 0xbfb8aa3b, v217
	v_mul_f32_e32 v218, 0xbfb8aa3b, v218
	v_mul_f32_e32 v219, 0xbfb8aa3b, v219
	v_mul_f32_e32 v220, 0xbfb8aa3b, v220
	v_mul_f32_e32 v221, 0xbfb8aa3b, v221
	v_mul_f32_e32 v222, 0xbfb8aa3b, v222
	v_mul_f32_e32 v223, 0xbfb8aa3b, v223
	v_mul_f32_e32 v224, 0xbfb8aa3b, v224
	v_mul_f32_e32 v225, 0xbfb8aa3b, v225
	v_mul_f32_e32 v226, 0xbfb8aa3b, v226
	v_mul_f32_e32 v227, 0xbfb8aa3b, v227
	v_mul_f32_e32 v228, 0xbfb8aa3b, v228
	v_mul_f32_e32 v229, 0xbfb8aa3b, v229
	v_pk_fma_f32 v[0:1], v[0:1], v[172:173], v[198:199] op_sel_hi:[1,0,1]
	v_pk_fma_f32 v[2:3], v[2:3], v[172:173], v[200:201] op_sel_hi:[1,0,1]
	v_pk_fma_f32 v[4:5], v[4:5], v[172:173], v[202:203] op_sel_hi:[1,0,1]
	v_pk_fma_f32 v[6:7], v[6:7], v[172:173], v[204:205] op_sel_hi:[1,0,1]
	v_pk_fma_f32 v[8:9], v[8:9], v[172:173], v[206:207] op_sel_hi:[1,0,1]
	v_pk_fma_f32 v[10:11], v[10:11], v[172:173], v[208:209] op_sel_hi:[1,0,1]
	v_pk_fma_f32 v[12:13], v[12:13], v[172:173], v[210:211] op_sel_hi:[1,0,1]
	v_pk_fma_f32 v[14:15], v[14:15], v[172:173], v[212:213] op_sel_hi:[1,0,1]
	v_pk_fma_f32 v[16:17], v[16:17], v[172:173], v[214:215] op_sel_hi:[1,0,1]
	v_pk_fma_f32 v[18:19], v[18:19], v[172:173], v[216:217] op_sel_hi:[1,0,1]
	v_pk_fma_f32 v[20:21], v[20:21], v[172:173], v[218:219] op_sel_hi:[1,0,1]
	v_pk_fma_f32 v[22:23], v[22:23], v[172:173], v[220:221] op_sel_hi:[1,0,1]
	v_pk_fma_f32 v[24:25], v[24:25], v[172:173], v[222:223] op_sel_hi:[1,0,1]
	v_pk_fma_f32 v[26:27], v[26:27], v[172:173], v[224:225] op_sel_hi:[1,0,1]
	v_pk_fma_f32 v[28:29], v[28:29], v[172:173], v[226:227] op_sel_hi:[1,0,1]
	v_pk_fma_f32 v[30:31], v[30:31], v[172:173], v[228:229] op_sel_hi:[1,0,1]
	v_exp_f32_e32 v0, v0
	v_exp_f32_e32 v1, v1
	v_exp_f32_e32 v2, v2
	v_exp_f32_e32 v3, v3
	v_exp_f32_e32 v4, v4
	v_exp_f32_e32 v5, v5
	v_exp_f32_e32 v6, v6
	v_exp_f32_e32 v7, v7
	v_exp_f32_e32 v8, v8
	v_exp_f32_e32 v9, v9
	v_exp_f32_e32 v10, v10
	v_exp_f32_e32 v11, v11
	v_exp_f32_e32 v12, v12
	v_exp_f32_e32 v13, v13
	v_exp_f32_e32 v14, v14
	v_exp_f32_e32 v15, v15
	v_exp_f32_e32 v16, v16
	v_exp_f32_e32 v17, v17
	v_exp_f32_e32 v18, v18
	v_exp_f32_e32 v19, v19
	v_exp_f32_e32 v20, v20
	v_exp_f32_e32 v21, v21
	v_exp_f32_e32 v22, v22
	v_exp_f32_e32 v23, v23
	v_exp_f32_e32 v24, v24
	v_exp_f32_e32 v25, v25
	v_exp_f32_e32 v26, v26
	v_exp_f32_e32 v27, v27
	v_exp_f32_e32 v28, v28
	v_exp_f32_e32 v29, v29
	v_exp_f32_e32 v30, v30
	v_exp_f32_e32 v31, v31
	v_pk_add_f32 v[0:1], v[0:1], 1.0 op_sel_hi:[1,0]
	v_pk_add_f32 v[2:3], v[2:3], 1.0 op_sel_hi:[1,0]
	v_pk_add_f32 v[4:5], v[4:5], 1.0 op_sel_hi:[1,0]
	v_pk_add_f32 v[6:7], v[6:7], 1.0 op_sel_hi:[1,0]
	v_pk_add_f32 v[8:9], v[8:9], 1.0 op_sel_hi:[1,0]
	v_pk_add_f32 v[10:11], v[10:11], 1.0 op_sel_hi:[1,0]
	v_pk_add_f32 v[12:13], v[12:13], 1.0 op_sel_hi:[1,0]
	v_pk_add_f32 v[14:15], v[14:15], 1.0 op_sel_hi:[1,0]
	v_pk_add_f32 v[16:17], v[16:17], 1.0 op_sel_hi:[1,0]
	v_pk_add_f32 v[18:19], v[18:19], 1.0 op_sel_hi:[1,0]
	v_pk_add_f32 v[20:21], v[20:21], 1.0 op_sel_hi:[1,0]
	v_pk_add_f32 v[22:23], v[22:23], 1.0 op_sel_hi:[1,0]
	v_pk_add_f32 v[24:25], v[24:25], 1.0 op_sel_hi:[1,0]
	v_pk_add_f32 v[26:27], v[26:27], 1.0 op_sel_hi:[1,0]
	v_pk_add_f32 v[28:29], v[28:29], 1.0 op_sel_hi:[1,0]
	v_pk_add_f32 v[30:31], v[30:31], 1.0 op_sel_hi:[1,0]
	v_rcp_f32_e32 v0, v0
	v_rcp_f32_e32 v1, v1
	v_rcp_f32_e32 v2, v2
	v_rcp_f32_e32 v3, v3
	v_rcp_f32_e32 v4, v4
	v_rcp_f32_e32 v5, v5
	v_rcp_f32_e32 v6, v6
	v_rcp_f32_e32 v7, v7
	v_rcp_f32_e32 v8, v8
	v_rcp_f32_e32 v9, v9
	v_rcp_f32_e32 v10, v10
	v_rcp_f32_e32 v11, v11
	v_rcp_f32_e32 v12, v12
	v_rcp_f32_e32 v13, v13
	v_rcp_f32_e32 v14, v14
	v_rcp_f32_e32 v15, v15
	v_rcp_f32_e32 v16, v16
	v_rcp_f32_e32 v17, v17
	v_rcp_f32_e32 v18, v18
	v_rcp_f32_e32 v19, v19
	v_rcp_f32_e32 v20, v20
	v_rcp_f32_e32 v21, v21
	v_rcp_f32_e32 v22, v22
	v_rcp_f32_e32 v23, v23
	v_rcp_f32_e32 v24, v24
	v_rcp_f32_e32 v25, v25
	v_rcp_f32_e32 v26, v26
	v_rcp_f32_e32 v27, v27
	v_rcp_f32_e32 v28, v28
	v_rcp_f32_e32 v29, v29
	v_rcp_f32_e32 v30, v30
	v_rcp_f32_e32 v31, v31
	s_nop 0
	v_cvt_pk_bf16_f32 v0, v0, v1
	v_cvt_pk_bf16_f32 v1, v2, v3
	v_cvt_pk_bf16_f32 v2, v4, v5
	v_cvt_pk_bf16_f32 v3, v6, v7
	v_cvt_pk_bf16_f32 v4, v8, v9
	v_cvt_pk_bf16_f32 v5, v10, v11
	v_cvt_pk_bf16_f32 v6, v12, v13
	v_cvt_pk_bf16_f32 v7, v14, v15
	v_cvt_pk_bf16_f32 v16, v16, v17
	v_cvt_pk_bf16_f32 v17, v18, v19
	v_cvt_pk_bf16_f32 v18, v20, v21
	v_cvt_pk_bf16_f32 v19, v22, v23
	v_cvt_pk_bf16_f32 v20, v24, v25
	v_cvt_pk_bf16_f32 v21, v26, v27
	v_cvt_pk_bf16_f32 v22, v28, v29
	v_cvt_pk_bf16_f32 v23, v30, v31
	v_permlane32_swap_b32_e32 v0, v2
	v_permlane32_swap_b32_e32 v1, v3
	v_permlane32_swap_b32_e32 v4, v6
	v_permlane32_swap_b32_e32 v5, v7
	v_permlane32_swap_b32_e32 v16, v18
	v_permlane32_swap_b32_e32 v17, v19
	v_permlane32_swap_b32_e32 v20, v22
	v_permlane32_swap_b32_e32 v21, v23
	global_store_dwordx4 v181, v[0:3], s[74:75] offset:0
	global_store_dwordx4 v181, v[4:7], s[74:75] offset:32
	global_store_dwordx4 v181, v[16:19], s[74:75] offset:64
	global_store_dwordx4 v181, v[20:23], s[74:75] offset:96
	s_add_u32 s74, s74, 0x44000
	s_addc_u32 s75, s75, 0
	v_pk_fma_f32 v[32:33], v[32:33], v[172:173], v[198:199] op_sel:[0,1,0] op_sel_hi:[1,1,1]
	v_pk_fma_f32 v[34:35], v[34:35], v[172:173], v[200:201] op_sel:[0,1,0] op_sel_hi:[1,1,1]
	v_pk_fma_f32 v[36:37], v[36:37], v[172:173], v[202:203] op_sel:[0,1,0] op_sel_hi:[1,1,1]
	v_pk_fma_f32 v[38:39], v[38:39], v[172:173], v[204:205] op_sel:[0,1,0] op_sel_hi:[1,1,1]
	v_pk_fma_f32 v[40:41], v[40:41], v[172:173], v[206:207] op_sel:[0,1,0] op_sel_hi:[1,1,1]
	v_pk_fma_f32 v[42:43], v[42:43], v[172:173], v[208:209] op_sel:[0,1,0] op_sel_hi:[1,1,1]
	v_pk_fma_f32 v[44:45], v[44:45], v[172:173], v[210:211] op_sel:[0,1,0] op_sel_hi:[1,1,1]
	v_pk_fma_f32 v[46:47], v[46:47], v[172:173], v[212:213] op_sel:[0,1,0] op_sel_hi:[1,1,1]
	v_pk_fma_f32 v[48:49], v[48:49], v[172:173], v[214:215] op_sel:[0,1,0] op_sel_hi:[1,1,1]
	v_pk_fma_f32 v[50:51], v[50:51], v[172:173], v[216:217] op_sel:[0,1,0] op_sel_hi:[1,1,1]
	v_pk_fma_f32 v[52:53], v[52:53], v[172:173], v[218:219] op_sel:[0,1,0] op_sel_hi:[1,1,1]
	v_pk_fma_f32 v[54:55], v[54:55], v[172:173], v[220:221] op_sel:[0,1,0] op_sel_hi:[1,1,1]
	v_pk_fma_f32 v[56:57], v[56:57], v[172:173], v[222:223] op_sel:[0,1,0] op_sel_hi:[1,1,1]
	v_pk_fma_f32 v[58:59], v[58:59], v[172:173], v[224:225] op_sel:[0,1,0] op_sel_hi:[1,1,1]
	v_pk_fma_f32 v[60:61], v[60:61], v[172:173], v[226:227] op_sel:[0,1,0] op_sel_hi:[1,1,1]
	v_pk_fma_f32 v[62:63], v[62:63], v[172:173], v[228:229] op_sel:[0,1,0] op_sel_hi:[1,1,1]
	v_exp_f32_e32 v32, v32
	v_exp_f32_e32 v33, v33
	v_exp_f32_e32 v34, v34
	v_exp_f32_e32 v35, v35
	v_exp_f32_e32 v36, v36
	v_exp_f32_e32 v37, v37
	v_exp_f32_e32 v38, v38
	v_exp_f32_e32 v39, v39
	v_exp_f32_e32 v40, v40
	v_exp_f32_e32 v41, v41
	v_exp_f32_e32 v42, v42
	v_exp_f32_e32 v43, v43
	v_exp_f32_e32 v44, v44
	v_exp_f32_e32 v45, v45
	v_exp_f32_e32 v46, v46
	v_exp_f32_e32 v47, v47
	v_exp_f32_e32 v48, v48
	v_exp_f32_e32 v49, v49
	v_exp_f32_e32 v50, v50
	v_exp_f32_e32 v51, v51
	v_exp_f32_e32 v52, v52
	v_exp_f32_e32 v53, v53
	v_exp_f32_e32 v54, v54
	v_exp_f32_e32 v55, v55
	v_exp_f32_e32 v56, v56
	v_exp_f32_e32 v57, v57
	v_exp_f32_e32 v58, v58
	v_exp_f32_e32 v59, v59
	v_exp_f32_e32 v60, v60
	v_exp_f32_e32 v61, v61
	v_exp_f32_e32 v62, v62
	v_exp_f32_e32 v63, v63
	v_pk_add_f32 v[32:33], v[32:33], 1.0 op_sel_hi:[1,0]
	v_pk_add_f32 v[34:35], v[34:35], 1.0 op_sel_hi:[1,0]
	v_pk_add_f32 v[36:37], v[36:37], 1.0 op_sel_hi:[1,0]
	v_pk_add_f32 v[38:39], v[38:39], 1.0 op_sel_hi:[1,0]
	v_pk_add_f32 v[40:41], v[40:41], 1.0 op_sel_hi:[1,0]
	v_pk_add_f32 v[42:43], v[42:43], 1.0 op_sel_hi:[1,0]
	v_pk_add_f32 v[44:45], v[44:45], 1.0 op_sel_hi:[1,0]
	v_pk_add_f32 v[46:47], v[46:47], 1.0 op_sel_hi:[1,0]
	v_pk_add_f32 v[48:49], v[48:49], 1.0 op_sel_hi:[1,0]
	v_pk_add_f32 v[50:51], v[50:51], 1.0 op_sel_hi:[1,0]
	v_pk_add_f32 v[52:53], v[52:53], 1.0 op_sel_hi:[1,0]
	v_pk_add_f32 v[54:55], v[54:55], 1.0 op_sel_hi:[1,0]
	v_pk_add_f32 v[56:57], v[56:57], 1.0 op_sel_hi:[1,0]
	v_pk_add_f32 v[58:59], v[58:59], 1.0 op_sel_hi:[1,0]
	v_pk_add_f32 v[60:61], v[60:61], 1.0 op_sel_hi:[1,0]
	v_pk_add_f32 v[62:63], v[62:63], 1.0 op_sel_hi:[1,0]
	v_rcp_f32_e32 v32, v32
	v_rcp_f32_e32 v33, v33
	v_rcp_f32_e32 v34, v34
	v_rcp_f32_e32 v35, v35
	v_rcp_f32_e32 v36, v36
	v_rcp_f32_e32 v37, v37
	v_rcp_f32_e32 v38, v38
	v_rcp_f32_e32 v39, v39
	v_rcp_f32_e32 v40, v40
	v_rcp_f32_e32 v41, v41
	v_rcp_f32_e32 v42, v42
	v_rcp_f32_e32 v43, v43
	v_rcp_f32_e32 v44, v44
	v_rcp_f32_e32 v45, v45
	v_rcp_f32_e32 v46, v46
	v_rcp_f32_e32 v47, v47
	v_rcp_f32_e32 v48, v48
	v_rcp_f32_e32 v49, v49
	v_rcp_f32_e32 v50, v50
	v_rcp_f32_e32 v51, v51
	v_rcp_f32_e32 v52, v52
	v_rcp_f32_e32 v53, v53
	v_rcp_f32_e32 v54, v54
	v_rcp_f32_e32 v55, v55
	v_rcp_f32_e32 v56, v56
	v_rcp_f32_e32 v57, v57
	v_rcp_f32_e32 v58, v58
	v_rcp_f32_e32 v59, v59
	v_rcp_f32_e32 v60, v60
	v_rcp_f32_e32 v61, v61
	v_rcp_f32_e32 v62, v62
	v_rcp_f32_e32 v63, v63
	s_nop 0
	v_cvt_pk_bf16_f32 v32, v32, v33
	v_cvt_pk_bf16_f32 v33, v34, v35
	v_cvt_pk_bf16_f32 v34, v36, v37
	v_cvt_pk_bf16_f32 v35, v38, v39
	v_cvt_pk_bf16_f32 v36, v40, v41
	v_cvt_pk_bf16_f32 v37, v42, v43
	v_cvt_pk_bf16_f32 v38, v44, v45
	v_cvt_pk_bf16_f32 v39, v46, v47
	v_cvt_pk_bf16_f32 v48, v48, v49
	v_cvt_pk_bf16_f32 v49, v50, v51
	v_cvt_pk_bf16_f32 v50, v52, v53
	v_cvt_pk_bf16_f32 v51, v54, v55
	v_cvt_pk_bf16_f32 v52, v56, v57
	v_cvt_pk_bf16_f32 v53, v58, v59
	v_cvt_pk_bf16_f32 v54, v60, v61
	v_cvt_pk_bf16_f32 v55, v62, v63
	v_permlane32_swap_b32_e32 v32, v34
	v_permlane32_swap_b32_e32 v33, v35
	v_permlane32_swap_b32_e32 v36, v38
	v_permlane32_swap_b32_e32 v37, v39
	v_permlane32_swap_b32_e32 v48, v50
	v_permlane32_swap_b32_e32 v49, v51
	v_permlane32_swap_b32_e32 v52, v54
	v_permlane32_swap_b32_e32 v53, v55
	global_store_dwordx4 v181, v[32:35], s[74:75] offset:0
	global_store_dwordx4 v181, v[36:39], s[74:75] offset:32
	global_store_dwordx4 v181, v[48:51], s[74:75] offset:64
	global_store_dwordx4 v181, v[52:55], s[74:75] offset:96
	s_add_u32 s74, s74, 0x44000
	s_addc_u32 s75, s75, 0
	v_pk_fma_f32 v[64:65], v[64:65], v[174:175], v[198:199] op_sel_hi:[1,0,1]
	v_pk_fma_f32 v[66:67], v[66:67], v[174:175], v[200:201] op_sel_hi:[1,0,1]
	v_pk_fma_f32 v[68:69], v[68:69], v[174:175], v[202:203] op_sel_hi:[1,0,1]
	v_pk_fma_f32 v[70:71], v[70:71], v[174:175], v[204:205] op_sel_hi:[1,0,1]
	v_pk_fma_f32 v[72:73], v[72:73], v[174:175], v[206:207] op_sel_hi:[1,0,1]
	v_pk_fma_f32 v[74:75], v[74:75], v[174:175], v[208:209] op_sel_hi:[1,0,1]
	v_pk_fma_f32 v[76:77], v[76:77], v[174:175], v[210:211] op_sel_hi:[1,0,1]
	v_pk_fma_f32 v[78:79], v[78:79], v[174:175], v[212:213] op_sel_hi:[1,0,1]
	v_pk_fma_f32 v[80:81], v[80:81], v[174:175], v[214:215] op_sel_hi:[1,0,1]
	v_pk_fma_f32 v[82:83], v[82:83], v[174:175], v[216:217] op_sel_hi:[1,0,1]
	v_pk_fma_f32 v[84:85], v[84:85], v[174:175], v[218:219] op_sel_hi:[1,0,1]
	v_pk_fma_f32 v[86:87], v[86:87], v[174:175], v[220:221] op_sel_hi:[1,0,1]
	v_pk_fma_f32 v[88:89], v[88:89], v[174:175], v[222:223] op_sel_hi:[1,0,1]
	v_pk_fma_f32 v[90:91], v[90:91], v[174:175], v[224:225] op_sel_hi:[1,0,1]
	v_pk_fma_f32 v[92:93], v[92:93], v[174:175], v[226:227] op_sel_hi:[1,0,1]
	v_pk_fma_f32 v[94:95], v[94:95], v[174:175], v[228:229] op_sel_hi:[1,0,1]
	v_exp_f32_e32 v64, v64
	v_exp_f32_e32 v65, v65
	v_exp_f32_e32 v66, v66
	v_exp_f32_e32 v67, v67
	v_exp_f32_e32 v68, v68
	v_exp_f32_e32 v69, v69
	v_exp_f32_e32 v70, v70
	v_exp_f32_e32 v71, v71
	v_exp_f32_e32 v72, v72
	v_exp_f32_e32 v73, v73
	v_exp_f32_e32 v74, v74
	v_exp_f32_e32 v75, v75
	v_exp_f32_e32 v76, v76
	v_exp_f32_e32 v77, v77
	v_exp_f32_e32 v78, v78
	v_exp_f32_e32 v79, v79
	v_exp_f32_e32 v80, v80
	v_exp_f32_e32 v81, v81
	v_exp_f32_e32 v82, v82
	v_exp_f32_e32 v83, v83
	v_exp_f32_e32 v84, v84
	v_exp_f32_e32 v85, v85
	v_exp_f32_e32 v86, v86
	v_exp_f32_e32 v87, v87
	v_exp_f32_e32 v88, v88
	v_exp_f32_e32 v89, v89
	v_exp_f32_e32 v90, v90
	v_exp_f32_e32 v91, v91
	v_exp_f32_e32 v92, v92
	v_exp_f32_e32 v93, v93
	v_exp_f32_e32 v94, v94
	v_exp_f32_e32 v95, v95
	v_pk_add_f32 v[64:65], v[64:65], 1.0 op_sel_hi:[1,0]
	v_pk_add_f32 v[66:67], v[66:67], 1.0 op_sel_hi:[1,0]
	v_pk_add_f32 v[68:69], v[68:69], 1.0 op_sel_hi:[1,0]
	v_pk_add_f32 v[70:71], v[70:71], 1.0 op_sel_hi:[1,0]
	v_pk_add_f32 v[72:73], v[72:73], 1.0 op_sel_hi:[1,0]
	v_pk_add_f32 v[74:75], v[74:75], 1.0 op_sel_hi:[1,0]
	v_pk_add_f32 v[76:77], v[76:77], 1.0 op_sel_hi:[1,0]
	v_pk_add_f32 v[78:79], v[78:79], 1.0 op_sel_hi:[1,0]
	v_pk_add_f32 v[80:81], v[80:81], 1.0 op_sel_hi:[1,0]
	v_pk_add_f32 v[82:83], v[82:83], 1.0 op_sel_hi:[1,0]
	v_pk_add_f32 v[84:85], v[84:85], 1.0 op_sel_hi:[1,0]
	v_pk_add_f32 v[86:87], v[86:87], 1.0 op_sel_hi:[1,0]
	v_pk_add_f32 v[88:89], v[88:89], 1.0 op_sel_hi:[1,0]
	v_pk_add_f32 v[90:91], v[90:91], 1.0 op_sel_hi:[1,0]
	v_pk_add_f32 v[92:93], v[92:93], 1.0 op_sel_hi:[1,0]
	v_pk_add_f32 v[94:95], v[94:95], 1.0 op_sel_hi:[1,0]
	v_rcp_f32_e32 v64, v64
	v_rcp_f32_e32 v65, v65
	v_rcp_f32_e32 v66, v66
	v_rcp_f32_e32 v67, v67
	v_rcp_f32_e32 v68, v68
	v_rcp_f32_e32 v69, v69
	v_rcp_f32_e32 v70, v70
	v_rcp_f32_e32 v71, v71
	v_rcp_f32_e32 v72, v72
	v_rcp_f32_e32 v73, v73
	v_rcp_f32_e32 v74, v74
	v_rcp_f32_e32 v75, v75
	v_rcp_f32_e32 v76, v76
	v_rcp_f32_e32 v77, v77
	v_rcp_f32_e32 v78, v78
	v_rcp_f32_e32 v79, v79
	v_rcp_f32_e32 v80, v80
	v_rcp_f32_e32 v81, v81
	v_rcp_f32_e32 v82, v82
	v_rcp_f32_e32 v83, v83
	v_rcp_f32_e32 v84, v84
	v_rcp_f32_e32 v85, v85
	v_rcp_f32_e32 v86, v86
	v_rcp_f32_e32 v87, v87
	v_rcp_f32_e32 v88, v88
	v_rcp_f32_e32 v89, v89
	v_rcp_f32_e32 v90, v90
	v_rcp_f32_e32 v91, v91
	v_rcp_f32_e32 v92, v92
	v_rcp_f32_e32 v93, v93
	v_rcp_f32_e32 v94, v94
	v_rcp_f32_e32 v95, v95
	s_nop 0
	v_cvt_pk_bf16_f32 v64, v64, v65
	v_cvt_pk_bf16_f32 v65, v66, v67
	v_cvt_pk_bf16_f32 v66, v68, v69
	v_cvt_pk_bf16_f32 v67, v70, v71
	v_cvt_pk_bf16_f32 v68, v72, v73
	v_cvt_pk_bf16_f32 v69, v74, v75
	v_cvt_pk_bf16_f32 v70, v76, v77
	v_cvt_pk_bf16_f32 v71, v78, v79
	v_cvt_pk_bf16_f32 v80, v80, v81
	v_cvt_pk_bf16_f32 v81, v82, v83
	v_cvt_pk_bf16_f32 v82, v84, v85
	v_cvt_pk_bf16_f32 v83, v86, v87
	v_cvt_pk_bf16_f32 v84, v88, v89
	v_cvt_pk_bf16_f32 v85, v90, v91
	v_cvt_pk_bf16_f32 v86, v92, v93
	v_cvt_pk_bf16_f32 v87, v94, v95
	v_permlane32_swap_b32_e32 v64, v66
	v_permlane32_swap_b32_e32 v65, v67
	v_permlane32_swap_b32_e32 v68, v70
	v_permlane32_swap_b32_e32 v69, v71
	v_permlane32_swap_b32_e32 v80, v82
	v_permlane32_swap_b32_e32 v81, v83
	v_permlane32_swap_b32_e32 v84, v86
	v_permlane32_swap_b32_e32 v85, v87
	global_store_dwordx4 v181, v[64:67], s[74:75] offset:0
	global_store_dwordx4 v181, v[68:71], s[74:75] offset:32
	global_store_dwordx4 v181, v[80:83], s[74:75] offset:64
	global_store_dwordx4 v181, v[84:87], s[74:75] offset:96
	s_add_u32 s74, s74, 0x44000
	s_addc_u32 s75, s75, 0
	v_pk_fma_f32 v[96:97], v[96:97], v[174:175], v[198:199] op_sel:[0,1,0] op_sel_hi:[1,1,1]
	v_pk_fma_f32 v[98:99], v[98:99], v[174:175], v[200:201] op_sel:[0,1,0] op_sel_hi:[1,1,1]
	v_pk_fma_f32 v[100:101], v[100:101], v[174:175], v[202:203] op_sel:[0,1,0] op_sel_hi:[1,1,1]
	v_pk_fma_f32 v[102:103], v[102:103], v[174:175], v[204:205] op_sel:[0,1,0] op_sel_hi:[1,1,1]
	v_pk_fma_f32 v[104:105], v[104:105], v[174:175], v[206:207] op_sel:[0,1,0] op_sel_hi:[1,1,1]
	v_pk_fma_f32 v[106:107], v[106:107], v[174:175], v[208:209] op_sel:[0,1,0] op_sel_hi:[1,1,1]
	v_pk_fma_f32 v[108:109], v[108:109], v[174:175], v[210:211] op_sel:[0,1,0] op_sel_hi:[1,1,1]
	v_pk_fma_f32 v[110:111], v[110:111], v[174:175], v[212:213] op_sel:[0,1,0] op_sel_hi:[1,1,1]
	v_pk_fma_f32 v[112:113], v[112:113], v[174:175], v[214:215] op_sel:[0,1,0] op_sel_hi:[1,1,1]
	v_pk_fma_f32 v[114:115], v[114:115], v[174:175], v[216:217] op_sel:[0,1,0] op_sel_hi:[1,1,1]
	v_pk_fma_f32 v[116:117], v[116:117], v[174:175], v[218:219] op_sel:[0,1,0] op_sel_hi:[1,1,1]
	v_pk_fma_f32 v[118:119], v[118:119], v[174:175], v[220:221] op_sel:[0,1,0] op_sel_hi:[1,1,1]
	v_pk_fma_f32 v[120:121], v[120:121], v[174:175], v[222:223] op_sel:[0,1,0] op_sel_hi:[1,1,1]
	v_pk_fma_f32 v[122:123], v[122:123], v[174:175], v[224:225] op_sel:[0,1,0] op_sel_hi:[1,1,1]
	v_pk_fma_f32 v[124:125], v[124:125], v[174:175], v[226:227] op_sel:[0,1,0] op_sel_hi:[1,1,1]
	v_pk_fma_f32 v[126:127], v[126:127], v[174:175], v[228:229] op_sel:[0,1,0] op_sel_hi:[1,1,1]
	v_exp_f32_e32 v96, v96
	v_exp_f32_e32 v97, v97
	v_exp_f32_e32 v98, v98
	v_exp_f32_e32 v99, v99
	v_exp_f32_e32 v100, v100
	v_exp_f32_e32 v101, v101
	v_exp_f32_e32 v102, v102
	v_exp_f32_e32 v103, v103
	v_exp_f32_e32 v104, v104
	v_exp_f32_e32 v105, v105
	v_exp_f32_e32 v106, v106
	v_exp_f32_e32 v107, v107
	v_exp_f32_e32 v108, v108
	v_exp_f32_e32 v109, v109
	v_exp_f32_e32 v110, v110
	v_exp_f32_e32 v111, v111
	v_exp_f32_e32 v112, v112
	v_exp_f32_e32 v113, v113
	v_exp_f32_e32 v114, v114
	v_exp_f32_e32 v115, v115
	v_exp_f32_e32 v116, v116
	v_exp_f32_e32 v117, v117
	v_exp_f32_e32 v118, v118
	v_exp_f32_e32 v119, v119
	v_exp_f32_e32 v120, v120
	v_exp_f32_e32 v121, v121
	v_exp_f32_e32 v122, v122
	v_exp_f32_e32 v123, v123
	v_exp_f32_e32 v124, v124
	v_exp_f32_e32 v125, v125
	v_exp_f32_e32 v126, v126
	v_exp_f32_e32 v127, v127
	v_pk_add_f32 v[96:97], v[96:97], 1.0 op_sel_hi:[1,0]
	v_pk_add_f32 v[98:99], v[98:99], 1.0 op_sel_hi:[1,0]
	v_pk_add_f32 v[100:101], v[100:101], 1.0 op_sel_hi:[1,0]
	v_pk_add_f32 v[102:103], v[102:103], 1.0 op_sel_hi:[1,0]
	v_pk_add_f32 v[104:105], v[104:105], 1.0 op_sel_hi:[1,0]
	v_pk_add_f32 v[106:107], v[106:107], 1.0 op_sel_hi:[1,0]
	v_pk_add_f32 v[108:109], v[108:109], 1.0 op_sel_hi:[1,0]
	v_pk_add_f32 v[110:111], v[110:111], 1.0 op_sel_hi:[1,0]
	v_pk_add_f32 v[112:113], v[112:113], 1.0 op_sel_hi:[1,0]
	v_pk_add_f32 v[114:115], v[114:115], 1.0 op_sel_hi:[1,0]
	v_pk_add_f32 v[116:117], v[116:117], 1.0 op_sel_hi:[1,0]
	v_pk_add_f32 v[118:119], v[118:119], 1.0 op_sel_hi:[1,0]
	v_pk_add_f32 v[120:121], v[120:121], 1.0 op_sel_hi:[1,0]
	v_pk_add_f32 v[122:123], v[122:123], 1.0 op_sel_hi:[1,0]
	v_pk_add_f32 v[124:125], v[124:125], 1.0 op_sel_hi:[1,0]
	v_pk_add_f32 v[126:127], v[126:127], 1.0 op_sel_hi:[1,0]
	v_rcp_f32_e32 v96, v96
	v_rcp_f32_e32 v97, v97
	v_rcp_f32_e32 v98, v98
	v_rcp_f32_e32 v99, v99
	v_rcp_f32_e32 v100, v100
	v_rcp_f32_e32 v101, v101
	v_rcp_f32_e32 v102, v102
	v_rcp_f32_e32 v103, v103
	v_rcp_f32_e32 v104, v104
	v_rcp_f32_e32 v105, v105
	v_rcp_f32_e32 v106, v106
	v_rcp_f32_e32 v107, v107
	v_rcp_f32_e32 v108, v108
	v_rcp_f32_e32 v109, v109
	v_rcp_f32_e32 v110, v110
	v_rcp_f32_e32 v111, v111
	v_rcp_f32_e32 v112, v112
	v_rcp_f32_e32 v113, v113
	v_rcp_f32_e32 v114, v114
	v_rcp_f32_e32 v115, v115
	v_rcp_f32_e32 v116, v116
	v_rcp_f32_e32 v117, v117
	v_rcp_f32_e32 v118, v118
	v_rcp_f32_e32 v119, v119
	v_rcp_f32_e32 v120, v120
	v_rcp_f32_e32 v121, v121
	v_rcp_f32_e32 v122, v122
	v_rcp_f32_e32 v123, v123
	v_rcp_f32_e32 v124, v124
	v_rcp_f32_e32 v125, v125
	v_rcp_f32_e32 v126, v126
	v_rcp_f32_e32 v127, v127
	s_nop 0
	v_cvt_pk_bf16_f32 v96, v96, v97
	v_cvt_pk_bf16_f32 v97, v98, v99
	v_cvt_pk_bf16_f32 v98, v100, v101
	v_cvt_pk_bf16_f32 v99, v102, v103
	v_cvt_pk_bf16_f32 v100, v104, v105
	v_cvt_pk_bf16_f32 v101, v106, v107
	v_cvt_pk_bf16_f32 v102, v108, v109
	v_cvt_pk_bf16_f32 v103, v110, v111
	v_cvt_pk_bf16_f32 v112, v112, v113
	v_cvt_pk_bf16_f32 v113, v114, v115
	v_cvt_pk_bf16_f32 v114, v116, v117
	v_cvt_pk_bf16_f32 v115, v118, v119
	v_cvt_pk_bf16_f32 v116, v120, v121
	v_cvt_pk_bf16_f32 v117, v122, v123
	v_cvt_pk_bf16_f32 v118, v124, v125
	v_cvt_pk_bf16_f32 v119, v126, v127
	v_permlane32_swap_b32_e32 v96, v98
	v_permlane32_swap_b32_e32 v97, v99
	v_permlane32_swap_b32_e32 v100, v102
	v_permlane32_swap_b32_e32 v101, v103
	v_permlane32_swap_b32_e32 v112, v114
	v_permlane32_swap_b32_e32 v113, v115
	v_permlane32_swap_b32_e32 v116, v118
	v_permlane32_swap_b32_e32 v117, v119
	global_store_dwordx4 v181, v[96:99], s[74:75] offset:0
	global_store_dwordx4 v181, v[100:103], s[74:75] offset:32
	global_store_dwordx4 v181, v[112:115], s[74:75] offset:64
	global_store_dwordx4 v181, v[116:119], s[74:75] offset:96
	s_branch .Lpe_ret_L0
.Lpe_vt_L0:
	s_lshl_b32 s35, s34, 2
	s_add_u32 s35, s35, s28
	s_add_u32 s36, s28, 6
	s_cmp_eq_u32 s25, 8
	s_cselect_b32 s35, s36, s35
	s_lshr_b32 s36, s29, 11
	s_mul_i32 s36, s36, 10
	s_add_u32 s36, s36, s35
	s_lshl_b32 s36, s36, 18
	s_and_b32 s37, s29, 0x7ff
	s_lshl_b32 s37, s37, 1
	s_add_u32 s36, s36, s37
	s_add_u32 s38, s72, 0x14920000
	s_addc_u32 s39, s73, 0
	s_add_u32 s38, s38, s36
	s_addc_u32 s39, s39, 0
	s_mul_i32 s36, s26, 10240
	s_add_u32 s36, s36, 0x10000
	v_lshlrev_b32_e32 v180, 1, v197
	v_mul_u32_u24_e32 v181, 36, v146
	v_add3_u32 v180, v180, v181, s36
	v_lshrrev_b32_e32 v181, 3, v179
	v_and_b32_e32 v146, 7, v179
	v_lshlrev_b32_e32 v146, 4, v146
	v_mul_u32_u24_e32 v198, 144, v181
	v_add3_u32 v198, v198, v146, s36
	v_lshl_add_u32 v199, v181, 12, v146
	s_waitcnt vmcnt(0)
	v_mov_b32_e32 v197, 0x358637bd
	v_pk_add_f32 v[128:129], v[128:129], v[130:131]
	v_pk_add_f32 v[132:133], v[132:133], v[134:135]
	v_pk_add_f32 v[136:137], v[136:137], v[138:139]
	v_pk_add_f32 v[140:141], v[140:141], v[142:143]
	v_pk_add_f32 v[164:165], v[164:165], v[166:167]
	v_pk_add_f32 v[168:169], v[168:169], v[170:171]
	v_pk_add_f32 v[246:247], v[246:247], v[248:249]
	v_pk_add_f32 v[250:251], v[250:251], v[252:253]
	v_pk_add_f32 v[128:129], v[128:129], v[132:133]
	v_pk_add_f32 v[136:137], v[136:137], v[140:141]
	v_pk_add_f32 v[164:165], v[164:165], v[168:169]
	v_pk_add_f32 v[246:247], v[246:247], v[250:251]
	v_add_f32_e32 v128, v128, v129
	v_add_f32_e32 v136, v136, v137
	v_add_f32_e32 v164, v164, v165
	v_add_f32_e32 v246, v246, v247
	v_fmamk_f32 v128, v128, 0x3a800000, v197
	v_fmamk_f32 v136, v136, 0x3a800000, v197
	v_fmamk_f32 v164, v164, 0x3a800000, v197
	v_fmamk_f32 v246, v246, 0x3a800000, v197
	v_rsq_f32_e32 v172, v128
	v_rsq_f32_e32 v173, v136
	v_rsq_f32_e32 v174, v164
	v_rsq_f32_e32 v175, v246
	s_nop 0
	s_add_u32 s76, s99, s90
	s_cmp_lt_u32 s76, 0x440
	s_cselect_b32 s80, 1, 0
	s_cselect_b32 s83, 0x200000, 0
	s_lshl_b32 s76, s24, 19
	s_lshl_b32 s77, s26, 16
	s_add_u32 s76, s76, s77
	s_and_b32 s77, s24, 7
	s_lshl_b32 s77, s77, 8
	s_add_u32 s76, s76, s77
	s_add_u32 s78, s72, 0xa120000
	s_addc_u32 s79, s73, 0
	s_add_u32 s78, s78, s76
	s_addc_u32 s79, s79, 0
	s_lshl_b32 s76, s25, 19
	s_add_u32 s76, s76, s83
	s_add_u32 s76, s76, s77
	s_lshl_b32 s77, s26, 16
	s_add_u32 s76, s76, s77
	s_add_u32 s82, s72, 0x0
	s_addc_u32 s83, s73, 0
	s_add_u32 s82, s82, s76
	s_addc_u32 s83, s83, 0
	s_lshl_b32 s76, s26, 12
	s_mov_b32 m0, s76
	s_nop 0
	global_load_lds_dwordx4 v145, s[78:79]
	s_add_u32 s78, s78, 0x4000
	s_addc_u32 s79, s79, 0
	s_add_u32 s76, s76, 0x400
	s_mov_b32 m0, s76
	s_nop 0
	global_load_lds_dwordx4 v185, s[78:79]
	s_add_u32 s78, s78, 0x4000
	s_addc_u32 s79, s79, 0
	s_add_u32 s76, s76, 0x400
	s_mov_b32 m0, s76
	s_nop 0
	global_load_lds_dwordx4 v145, s[78:79]
	s_add_u32 s78, s78, 0x4000
	s_addc_u32 s79, s79, 0
	s_add_u32 s76, s76, 0x400
	s_mov_b32 m0, s76
	s_nop 0
	global_load_lds_dwordx4 v185, s[78:79]
	s_add_u32 s78, s78, 0x4000
	s_addc_u32 s79, s79, 0
	s_add_u32 s76, s76, 0x400
	s_add_u32 s76, s76, 0x7000
	s_mov_b32 m0, s76
	s_nop 0
	global_load_lds_dwordx4 v145, s[82:83]
	s_add_u32 s82, s82, 0x4000
	s_addc_u32 s83, s83, 0
	s_add_u32 s76, s76, 0x400
	s_mov_b32 m0, s76
	s_nop 0
	global_load_lds_dwordx4 v185, s[82:83]
	s_add_u32 s82, s82, 0x4000
	s_addc_u32 s83, s83, 0
	s_add_u32 s76, s76, 0x400
	s_mov_b32 m0, s76
	s_nop 0
	global_load_lds_dwordx4 v145, s[82:83]
	s_add_u32 s82, s82, 0x4000
	s_addc_u32 s83, s83, 0
	s_add_u32 s76, s76, 0x400
	s_mov_b32 m0, s76
	s_nop 0
	global_load_lds_dwordx4 v185, s[82:83]
	s_add_u32 s82, s82, 0x4000
	s_addc_u32 s83, s83, 0
	s_add_u32 s76, s76, 0x400
	s_and_b32 s77, s24, 7
	s_lshl_b32 s77, s77, 8
	s_add_u32 s76, s77, 0x10000
	s_sub_u32 s78, s78, s76
	s_subb_u32 s79, s79, 0
	s_sub_u32 s82, s82, s76
	s_subb_u32 s83, s83, 0
	s_sub_u32 s76, s78, s82
	v_lshrrev_b32_e32 v196, 5, v179
	v_add_u32_e32 v196, -1, v196
	v_and_b32_e32 v196, s76, v196
	v_and_b32_e32 v194, 31, v179
	v_lshl_add_u32 v194, v194, 11, v196
	s_add_u32 s76, s77, 0x80
	s_and_b32 s76, s76, 0x7ff
	s_add_u32 s78, s82, s76
	s_addc_u32 s79, s83, 0
	global_load_dword v195, v194, s[78:79]
	s_add_u32 s76, s77, 0x100
	s_and_b32 s76, s76, 0x7ff
	s_add_u32 s78, s82, s76
	s_addc_u32 s79, s83, 0
	global_load_dword v195, v194, s[78:79]
	s_add_u32 s76, s77, 0x180
	s_and_b32 s76, s76, 0x7ff
	s_add_u32 s78, s82, s76
	s_addc_u32 s79, s83, 0
	global_load_dword v195, v194, s[78:79]
	s_add_u32 s76, s77, 0x200
	s_and_b32 s76, s76, 0x7ff
	s_add_u32 s78, s82, s76
	s_addc_u32 s79, s83, 0
	global_load_dword v195, v194, s[78:79]
	v_pk_mul_f32 v[0:1], v[0:1], v[172:173] op_sel_hi:[1,0]
	v_pk_mul_f32 v[2:3], v[2:3], v[172:173] op_sel_hi:[1,0]
	v_pk_mul_f32 v[4:5], v[4:5], v[172:173] op_sel_hi:[1,0]
	v_pk_mul_f32 v[6:7], v[6:7], v[172:173] op_sel_hi:[1,0]
	v_pk_mul_f32 v[8:9], v[8:9], v[172:173] op_sel_hi:[1,0]
	v_pk_mul_f32 v[10:11], v[10:11], v[172:173] op_sel_hi:[1,0]
	v_pk_mul_f32 v[12:13], v[12:13], v[172:173] op_sel_hi:[1,0]
	v_pk_mul_f32 v[14:15], v[14:15], v[172:173] op_sel_hi:[1,0]
	v_pk_mul_f32 v[16:17], v[16:17], v[172:173] op_sel_hi:[1,0]
	v_pk_mul_f32 v[18:19], v[18:19], v[172:173] op_sel_hi:[1,0]
	v_pk_mul_f32 v[20:21], v[20:21], v[172:173] op_sel_hi:[1,0]
	v_pk_mul_f32 v[22:23], v[22:23], v[172:173] op_sel_hi:[1,0]
	v_pk_mul_f32 v[24:25], v[24:25], v[172:173] op_sel_hi:[1,0]
	v_pk_mul_f32 v[26:27], v[26:27], v[172:173] op_sel_hi:[1,0]
	v_pk_mul_f32 v[28:29], v[28:29], v[172:173] op_sel_hi:[1,0]
	v_pk_mul_f32 v[30:31], v[30:31], v[172:173] op_sel_hi:[1,0]
	v_pk_mul_f32 v[32:33], v[32:33], v[172:173] op_sel:[0,1] op_sel_hi:[1,1]
	v_pk_mul_f32 v[34:35], v[34:35], v[172:173] op_sel:[0,1] op_sel_hi:[1,1]
	v_pk_mul_f32 v[36:37], v[36:37], v[172:173] op_sel:[0,1] op_sel_hi:[1,1]
	v_pk_mul_f32 v[38:39], v[38:39], v[172:173] op_sel:[0,1] op_sel_hi:[1,1]
	v_pk_mul_f32 v[40:41], v[40:41], v[172:173] op_sel:[0,1] op_sel_hi:[1,1]
	v_pk_mul_f32 v[42:43], v[42:43], v[172:173] op_sel:[0,1] op_sel_hi:[1,1]
	v_pk_mul_f32 v[44:45], v[44:45], v[172:173] op_sel:[0,1] op_sel_hi:[1,1]
	v_pk_mul_f32 v[46:47], v[46:47], v[172:173] op_sel:[0,1] op_sel_hi:[1,1]
	v_pk_mul_f32 v[48:49], v[48:49], v[172:173] op_sel:[0,1] op_sel_hi:[1,1]
	v_pk_mul_f32 v[50:51], v[50:51], v[172:173] op_sel:[0,1] op_sel_hi:[1,1]
	v_pk_mul_f32 v[52:53], v[52:53], v[172:173] op_sel:[0,1] op_sel_hi:[1,1]
	v_pk_mul_f32 v[54:55], v[54:55], v[172:173] op_sel:[0,1] op_sel_hi:[1,1]
	v_pk_mul_f32 v[56:57], v[56:57], v[172:173] op_sel:[0,1] op_sel_hi:[1,1]
	v_pk_mul_f32 v[58:59], v[58:59], v[172:173] op_sel:[0,1] op_sel_hi:[1,1]
	v_pk_mul_f32 v[60:61], v[60:61], v[172:173] op_sel:[0,1] op_sel_hi:[1,1]
	v_pk_mul_f32 v[62:63], v[62:63], v[172:173] op_sel:[0,1] op_sel_hi:[1,1]
	v_pk_mul_f32 v[64:65], v[64:65], v[174:175] op_sel_hi:[1,0]
	v_pk_mul_f32 v[66:67], v[66:67], v[174:175] op_sel_hi:[1,0]
	v_pk_mul_f32 v[68:69], v[68:69], v[174:175] op_sel_hi:[1,0]
	v_pk_mul_f32 v[70:71], v[70:71], v[174:175] op_sel_hi:[1,0]
	v_pk_mul_f32 v[72:73], v[72:73], v[174:175] op_sel_hi:[1,0]
	v_pk_mul_f32 v[74:75], v[74:75], v[174:175] op_sel_hi:[1,0]
	v_pk_mul_f32 v[76:77], v[76:77], v[174:175] op_sel_hi:[1,0]
	v_pk_mul_f32 v[78:79], v[78:79], v[174:175] op_sel_hi:[1,0]
	v_pk_mul_f32 v[80:81], v[80:81], v[174:175] op_sel_hi:[1,0]
	v_pk_mul_f32 v[82:83], v[82:83], v[174:175] op_sel_hi:[1,0]
	v_pk_mul_f32 v[84:85], v[84:85], v[174:175] op_sel_hi:[1,0]
	v_pk_mul_f32 v[86:87], v[86:87], v[174:175] op_sel_hi:[1,0]
	v_pk_mul_f32 v[88:89], v[88:89], v[174:175] op_sel_hi:[1,0]
	v_pk_mul_f32 v[90:91], v[90:91], v[174:175] op_sel_hi:[1,0]
	v_pk_mul_f32 v[92:93], v[92:93], v[174:175] op_sel_hi:[1,0]
	v_pk_mul_f32 v[94:95], v[94:95], v[174:175] op_sel_hi:[1,0]
	v_pk_mul_f32 v[96:97], v[96:97], v[174:175] op_sel:[0,1] op_sel_hi:[1,1]
	v_pk_mul_f32 v[98:99], v[98:99], v[174:175] op_sel:[0,1] op_sel_hi:[1,1]
	v_pk_mul_f32 v[100:101], v[100:101], v[174:175] op_sel:[0,1] op_sel_hi:[1,1]
	v_pk_mul_f32 v[102:103], v[102:103], v[174:175] op_sel:[0,1] op_sel_hi:[1,1]
	v_pk_mul_f32 v[104:105], v[104:105], v[174:175] op_sel:[0,1] op_sel_hi:[1,1]
	v_pk_mul_f32 v[106:107], v[106:107], v[174:175] op_sel:[0,1] op_sel_hi:[1,1]
	v_pk_mul_f32 v[108:109], v[108:109], v[174:175] op_sel:[0,1] op_sel_hi:[1,1]
	v_pk_mul_f32 v[110:111], v[110:111], v[174:175] op_sel:[0,1] op_sel_hi:[1,1]
	v_pk_mul_f32 v[112:113], v[112:113], v[174:175] op_sel:[0,1] op_sel_hi:[1,1]
	v_pk_mul_f32 v[114:115], v[114:115], v[174:175] op_sel:[0,1] op_sel_hi:[1,1]
	v_pk_mul_f32 v[116:117], v[116:117], v[174:175] op_sel:[0,1] op_sel_hi:[1,1]
	v_pk_mul_f32 v[118:119], v[118:119], v[174:175] op_sel:[0,1] op_sel_hi:[1,1]
	v_pk_mul_f32 v[120:121], v[120:121], v[174:175] op_sel:[0,1] op_sel_hi:[1,1]
	v_pk_mul_f32 v[122:123], v[122:123], v[174:175] op_sel:[0,1] op_sel_hi:[1,1]
	v_pk_mul_f32 v[124:125], v[124:125], v[174:175] op_sel:[0,1] op_sel_hi:[1,1]
	v_pk_mul_f32 v[126:127], v[126:127], v[174:175] op_sel:[0,1] op_sel_hi:[1,1]
	v_cvt_pk_bf16_f32 v0, v0, v1
	v_cvt_pk_bf16_f32 v1, v2, v3
	v_cvt_pk_bf16_f32 v2, v4, v5
	v_cvt_pk_bf16_f32 v3, v6, v7
	v_cvt_pk_bf16_f32 v4, v8, v9
	v_cvt_pk_bf16_f32 v5, v10, v11
	v_cvt_pk_bf16_f32 v6, v12, v13
	v_cvt_pk_bf16_f32 v7, v14, v15
	ds_write_b16 v180, v0 offset:0
	ds_write_b16_d16_hi v180, v0 offset:144
	ds_write_b16 v180, v1 offset:288
	ds_write_b16_d16_hi v180, v1 offset:432
	ds_write_b16 v180, v2 offset:1152
	ds_write_b16_d16_hi v180, v2 offset:1296
	ds_write_b16 v180, v3 offset:1440
	ds_write_b16_d16_hi v180, v3 offset:1584
	ds_write_b16 v180, v4 offset:2304
	ds_write_b16_d16_hi v180, v4 offset:2448
	ds_write_b16 v180, v5 offset:2592
	ds_write_b16_d16_hi v180, v5 offset:2736
	ds_write_b16 v180, v6 offset:3456
	ds_write_b16_d16_hi v180, v6 offset:3600
	ds_write_b16 v180, v7 offset:3744
	ds_write_b16_d16_hi v180, v7 offset:3888
	v_cvt_pk_bf16_f32 v16, v16, v17
	v_cvt_pk_bf16_f32 v17, v18, v19
	v_cvt_pk_bf16_f32 v18, v20, v21
	v_cvt_pk_bf16_f32 v19, v22, v23
	v_cvt_pk_bf16_f32 v20, v24, v25
	v_cvt_pk_bf16_f32 v21, v26, v27
	v_cvt_pk_bf16_f32 v22, v28, v29
	v_cvt_pk_bf16_f32 v23, v30, v31
	ds_write_b16 v180, v16 offset:4608
	ds_write_b16_d16_hi v180, v16 offset:4752
	ds_write_b16 v180, v17 offset:4896
	ds_write_b16_d16_hi v180, v17 offset:5040
	ds_write_b16 v180, v18 offset:5760
	ds_write_b16_d16_hi v180, v18 offset:5904
	ds_write_b16 v180, v19 offset:6048
	ds_write_b16_d16_hi v180, v19 offset:6192
	ds_write_b16 v180, v20 offset:6912
	ds_write_b16_d16_hi v180, v20 offset:7056
	ds_write_b16 v180, v21 offset:7200
	ds_write_b16_d16_hi v180, v21 offset:7344
	ds_write_b16 v180, v22 offset:8064
	ds_write_b16_d16_hi v180, v22 offset:8208
	ds_write_b16 v180, v23 offset:8352
	ds_write_b16_d16_hi v180, v23 offset:8496
	v_cvt_pk_bf16_f32 v32, v32, v33
	v_cvt_pk_bf16_f32 v33, v34, v35
	v_cvt_pk_bf16_f32 v34, v36, v37
	v_cvt_pk_bf16_f32 v35, v38, v39
	v_cvt_pk_bf16_f32 v36, v40, v41
	v_cvt_pk_bf16_f32 v37, v42, v43
	v_cvt_pk_bf16_f32 v38, v44, v45
	v_cvt_pk_bf16_f32 v39, v46, v47
	ds_write_b16 v180, v32 offset:64
	ds_write_b16_d16_hi v180, v32 offset:208
	ds_write_b16 v180, v33 offset:352
	ds_write_b16_d16_hi v180, v33 offset:496
	ds_write_b16 v180, v34 offset:1216
	ds_write_b16_d16_hi v180, v34 offset:1360
	ds_write_b16 v180, v35 offset:1504
	ds_write_b16_d16_hi v180, v35 offset:1648
	ds_write_b16 v180, v36 offset:2368
	ds_write_b16_d16_hi v180, v36 offset:2512
	ds_write_b16 v180, v37 offset:2656
	ds_write_b16_d16_hi v180, v37 offset:2800
	ds_write_b16 v180, v38 offset:3520
	ds_write_b16_d16_hi v180, v38 offset:3664
	ds_write_b16 v180, v39 offset:3808
	ds_write_b16_d16_hi v180, v39 offset:3952
	v_cvt_pk_bf16_f32 v48, v48, v49
	v_cvt_pk_bf16_f32 v49, v50, v51
	v_cvt_pk_bf16_f32 v50, v52, v53
	v_cvt_pk_bf16_f32 v51, v54, v55
	v_cvt_pk_bf16_f32 v52, v56, v57
	v_cvt_pk_bf16_f32 v53, v58, v59
	v_cvt_pk_bf16_f32 v54, v60, v61
	v_cvt_pk_bf16_f32 v55, v62, v63
	ds_write_b16 v180, v48 offset:4672
	ds_write_b16_d16_hi v180, v48 offset:4816
	ds_write_b16 v180, v49 offset:4960
	ds_write_b16_d16_hi v180, v49 offset:5104
	ds_write_b16 v180, v50 offset:5824
	ds_write_b16_d16_hi v180, v50 offset:5968
	ds_write_b16 v180, v51 offset:6112
	ds_write_b16_d16_hi v180, v51 offset:6256
	ds_write_b16 v180, v52 offset:6976
	ds_write_b16_d16_hi v180, v52 offset:7120
	ds_write_b16 v180, v53 offset:7264
	ds_write_b16_d16_hi v180, v53 offset:7408
	ds_write_b16 v180, v54 offset:8128
	ds_write_b16_d16_hi v180, v54 offset:8272
	ds_write_b16 v180, v55 offset:8416
	ds_write_b16_d16_hi v180, v55 offset:8560
	s_waitcnt lgkmcnt(0)
	ds_read_b128 v[0:3], v198 offset:0
	ds_read_b128 v[4:7], v198 offset:1152
	ds_read_b128 v[8:11], v198 offset:2304
	ds_read_b128 v[12:15], v198 offset:3456
	ds_read_b128 v[16:19], v198 offset:4608
	ds_read_b128 v[20:23], v198 offset:5760
	ds_read_b128 v[24:27], v198 offset:6912
	ds_read_b128 v[28:31], v198 offset:8064
	s_waitcnt lgkmcnt(7)
	global_store_dwordx4 v199, v[0:3], s[38:39]
	s_add_u32 s38, s38, 0x8000
	s_addc_u32 s39, s39, 0
	s_waitcnt lgkmcnt(6)
	global_store_dwordx4 v199, v[4:7], s[38:39]
	s_add_u32 s38, s38, 0x8000
	s_addc_u32 s39, s39, 0
	s_waitcnt lgkmcnt(5)
	global_store_dwordx4 v199, v[8:11], s[38:39]
	s_add_u32 s38, s38, 0x8000
	s_addc_u32 s39, s39, 0
	s_waitcnt lgkmcnt(4)
	global_store_dwordx4 v199, v[12:15], s[38:39]
	s_add_u32 s38, s38, 0x8000
	s_addc_u32 s39, s39, 0
	s_waitcnt lgkmcnt(3)
	global_store_dwordx4 v199, v[16:19], s[38:39]
	s_add_u32 s38, s38, 0x8000
	s_addc_u32 s39, s39, 0
	s_waitcnt lgkmcnt(2)
	global_store_dwordx4 v199, v[20:23], s[38:39]
	s_add_u32 s38, s38, 0x8000
	s_addc_u32 s39, s39, 0
	s_waitcnt lgkmcnt(1)
	global_store_dwordx4 v199, v[24:27], s[38:39]
	s_add_u32 s38, s38, 0x8000
	s_addc_u32 s39, s39, 0
	s_waitcnt lgkmcnt(0)
	global_store_dwordx4 v199, v[28:31], s[38:39]
	s_sub_u32 s38, s38, 229248
	s_subb_u32 s39, s39, 0
	v_cvt_pk_bf16_f32 v64, v64, v65
	v_cvt_pk_bf16_f32 v65, v66, v67
	v_cvt_pk_bf16_f32 v66, v68, v69
	v_cvt_pk_bf16_f32 v67, v70, v71
	v_cvt_pk_bf16_f32 v68, v72, v73
	v_cvt_pk_bf16_f32 v69, v74, v75
	v_cvt_pk_bf16_f32 v70, v76, v77
	v_cvt_pk_bf16_f32 v71, v78, v79
	ds_write_b16 v180, v64 offset:0
	ds_write_b16_d16_hi v180, v64 offset:144
	ds_write_b16 v180, v65 offset:288
	ds_write_b16_d16_hi v180, v65 offset:432
	ds_write_b16 v180, v66 offset:1152
	ds_write_b16_d16_hi v180, v66 offset:1296
	ds_write_b16 v180, v67 offset:1440
	ds_write_b16_d16_hi v180, v67 offset:1584
	ds_write_b16 v180, v68 offset:2304
	ds_write_b16_d16_hi v180, v68 offset:2448
	ds_write_b16 v180, v69 offset:2592
	ds_write_b16_d16_hi v180, v69 offset:2736
	ds_write_b16 v180, v70 offset:3456
	ds_write_b16_d16_hi v180, v70 offset:3600
	ds_write_b16 v180, v71 offset:3744
	ds_write_b16_d16_hi v180, v71 offset:3888
	v_cvt_pk_bf16_f32 v80, v80, v81
	v_cvt_pk_bf16_f32 v81, v82, v83
	v_cvt_pk_bf16_f32 v82, v84, v85
	v_cvt_pk_bf16_f32 v83, v86, v87
	v_cvt_pk_bf16_f32 v84, v88, v89
	v_cvt_pk_bf16_f32 v85, v90, v91
	v_cvt_pk_bf16_f32 v86, v92, v93
	v_cvt_pk_bf16_f32 v87, v94, v95
	ds_write_b16 v180, v80 offset:4608
	ds_write_b16_d16_hi v180, v80 offset:4752
	ds_write_b16 v180, v81 offset:4896
	ds_write_b16_d16_hi v180, v81 offset:5040
	ds_write_b16 v180, v82 offset:5760
	ds_write_b16_d16_hi v180, v82 offset:5904
	ds_write_b16 v180, v83 offset:6048
	ds_write_b16_d16_hi v180, v83 offset:6192
	ds_write_b16 v180, v84 offset:6912
	ds_write_b16_d16_hi v180, v84 offset:7056
	ds_write_b16 v180, v85 offset:7200
	ds_write_b16_d16_hi v180, v85 offset:7344
	ds_write_b16 v180, v86 offset:8064
	ds_write_b16_d16_hi v180, v86 offset:8208
	ds_write_b16 v180, v87 offset:8352
	ds_write_b16_d16_hi v180, v87 offset:8496
	v_cvt_pk_bf16_f32 v96, v96, v97
	v_cvt_pk_bf16_f32 v97, v98, v99
	v_cvt_pk_bf16_f32 v98, v100, v101
	v_cvt_pk_bf16_f32 v99, v102, v103
	v_cvt_pk_bf16_f32 v100, v104, v105
	v_cvt_pk_bf16_f32 v101, v106, v107
	v_cvt_pk_bf16_f32 v102, v108, v109
	v_cvt_pk_bf16_f32 v103, v110, v111
	ds_write_b16 v180, v96 offset:64
	ds_write_b16_d16_hi v180, v96 offset:208
	ds_write_b16 v180, v97 offset:352
	ds_write_b16_d16_hi v180, v97 offset:496
	ds_write_b16 v180, v98 offset:1216
	ds_write_b16_d16_hi v180, v98 offset:1360
	ds_write_b16 v180, v99 offset:1504
	ds_write_b16_d16_hi v180, v99 offset:1648
	ds_write_b16 v180, v100 offset:2368
	ds_write_b16_d16_hi v180, v100 offset:2512
	ds_write_b16 v180, v101 offset:2656
	ds_write_b16_d16_hi v180, v101 offset:2800
	ds_write_b16 v180, v102 offset:3520
	ds_write_b16_d16_hi v180, v102 offset:3664
	ds_write_b16 v180, v103 offset:3808
	ds_write_b16_d16_hi v180, v103 offset:3952
	v_cvt_pk_bf16_f32 v112, v112, v113
	v_cvt_pk_bf16_f32 v113, v114, v115
	v_cvt_pk_bf16_f32 v114, v116, v117
	v_cvt_pk_bf16_f32 v115, v118, v119
	v_cvt_pk_bf16_f32 v116, v120, v121
	v_cvt_pk_bf16_f32 v117, v122, v123
	v_cvt_pk_bf16_f32 v118, v124, v125
	v_cvt_pk_bf16_f32 v119, v126, v127
	ds_write_b16 v180, v112 offset:4672
	ds_write_b16_d16_hi v180, v112 offset:4816
	ds_write_b16 v180, v113 offset:4960
	ds_write_b16_d16_hi v180, v113 offset:5104
	ds_write_b16 v180, v114 offset:5824
	ds_write_b16_d16_hi v180, v114 offset:5968
	ds_write_b16 v180, v115 offset:6112
	ds_write_b16_d16_hi v180, v115 offset:6256
	ds_write_b16 v180, v116 offset:6976
	ds_write_b16_d16_hi v180, v116 offset:7120
	ds_write_b16 v180, v117 offset:7264
	ds_write_b16_d16_hi v180, v117 offset:7408
	ds_write_b16 v180, v118 offset:8128
	ds_write_b16_d16_hi v180, v118 offset:8272
	ds_write_b16 v180, v119 offset:8416
	ds_write_b16_d16_hi v180, v119 offset:8560
	s_waitcnt lgkmcnt(0)
	ds_read_b128 v[64:67], v198 offset:0
	ds_read_b128 v[68:71], v198 offset:1152
	ds_read_b128 v[72:75], v198 offset:2304
	ds_read_b128 v[76:79], v198 offset:3456
	ds_read_b128 v[80:83], v198 offset:4608
	ds_read_b128 v[84:87], v198 offset:5760
	ds_read_b128 v[88:91], v198 offset:6912
	ds_read_b128 v[92:95], v198 offset:8064
	s_waitcnt lgkmcnt(7)
	global_store_dwordx4 v199, v[64:67], s[38:39]
	s_add_u32 s38, s38, 0x8000
	s_addc_u32 s39, s39, 0
	s_waitcnt lgkmcnt(6)
	global_store_dwordx4 v199, v[68:71], s[38:39]
	s_add_u32 s38, s38, 0x8000
	s_addc_u32 s39, s39, 0
	s_waitcnt lgkmcnt(5)
	global_store_dwordx4 v199, v[72:75], s[38:39]
	s_add_u32 s38, s38, 0x8000
	s_addc_u32 s39, s39, 0
	s_waitcnt lgkmcnt(4)
	global_store_dwordx4 v199, v[76:79], s[38:39]
	s_add_u32 s38, s38, 0x8000
	s_addc_u32 s39, s39, 0
	s_waitcnt lgkmcnt(3)
	global_store_dwordx4 v199, v[80:83], s[38:39]
	s_add_u32 s38, s38, 0x8000
	s_addc_u32 s39, s39, 0
	s_waitcnt lgkmcnt(2)
	global_store_dwordx4 v199, v[84:87], s[38:39]
	s_add_u32 s38, s38, 0x8000
	s_addc_u32 s39, s39, 0
	s_waitcnt lgkmcnt(1)
	global_store_dwordx4 v199, v[88:91], s[38:39]
	s_add_u32 s38, s38, 0x8000
	s_addc_u32 s39, s39, 0
	s_waitcnt lgkmcnt(0)
	global_store_dwordx4 v199, v[92:95], s[38:39]

.Lpf_skip_L1:
	s_sub_u32 s6, s6, s81
	s_subb_u32 s7, s7, 0
	s_sub_u32 s4, s4, s81
	s_subb_u32 s5, s5, 0
	s_add_u32 s27, s4, 0xc000
	s_addc_u32 s28, s5, 0
	s_add_u32 s29, s4, 0x8000
	s_addc_u32 s30, s5, 0
	s_add_u32 s31, s4, 0x4000
	s_addc_u32 s34, s5, 0
	s_add_u32 s35, s4, 0x0
	s_addc_u32 s36, s5, 0
	s_add_u32 s37, s6, 0xc000
	s_addc_u32 s38, s7, 0
	s_add_u32 s39, s6, 0x8000
	s_addc_u32 s40, s7, 0
	s_add_u32 s41, s6, 0x4000
	s_addc_u32 s42, s7, 0
	s_add_u32 s43, s6, 0x0
	s_addc_u32 s44, s7, 0
	s_mov_b64 s[4:5], 0
	s_mov_b32 s46, s17
	s_mov_b32 s45, s17
	v_mov_b32_e32 v0, v145
	v_mov_b32_e32 v1, v145
	v_mov_b32_e32 v2, v145
	v_mov_b32_e32 v3, v145
	v_mov_b32_e32 v4, v145
	v_mov_b32_e32 v5, v145
	v_mov_b32_e32 v6, v145
	v_mov_b32_e32 v7, v145
	v_mov_b32_e32 v8, v145
	v_mov_b32_e32 v9, v145
	v_mov_b32_e32 v10, v145
	v_mov_b32_e32 v11, v145
	v_mov_b32_e32 v12, v145
	v_mov_b32_e32 v13, v145
	v_mov_b32_e32 v14, v145
	v_mov_b32_e32 v15, v145
	v_mov_b32_e32 v16, v145
	v_mov_b32_e32 v17, v145
	v_mov_b32_e32 v18, v145
	v_mov_b32_e32 v19, v145
	v_mov_b32_e32 v20, v145
	v_mov_b32_e32 v21, v145
	v_mov_b32_e32 v22, v145
	v_mov_b32_e32 v23, v145
	v_mov_b32_e32 v24, v145
	v_mov_b32_e32 v25, v145
	v_mov_b32_e32 v26, v145
	v_mov_b32_e32 v27, v145
	v_mov_b32_e32 v28, v145
	v_mov_b32_e32 v29, v145
	v_mov_b32_e32 v30, v145
	v_mov_b32_e32 v31, v145
	v_mov_b32_e32 v32, v145
	v_mov_b32_e32 v33, v145
	v_mov_b32_e32 v34, v145
	v_mov_b32_e32 v35, v145
	v_mov_b32_e32 v36, v145
	v_mov_b32_e32 v37, v145
	v_mov_b32_e32 v38, v145
	v_mov_b32_e32 v39, v145
	v_mov_b32_e32 v40, v145
	v_mov_b32_e32 v41, v145
	v_mov_b32_e32 v42, v145
	v_mov_b32_e32 v43, v145
	v_mov_b32_e32 v44, v145
	v_mov_b32_e32 v45, v145
	v_mov_b32_e32 v46, v145
	v_mov_b32_e32 v47, v145
	v_mov_b32_e32 v48, v145
	v_mov_b32_e32 v49, v145
	v_mov_b32_e32 v50, v145
	v_mov_b32_e32 v51, v145
	v_mov_b32_e32 v52, v145
	v_mov_b32_e32 v53, v145
	v_mov_b32_e32 v54, v145
	v_mov_b32_e32 v55, v145
	v_mov_b32_e32 v56, v145
	v_mov_b32_e32 v57, v145
	v_mov_b32_e32 v58, v145
	v_mov_b32_e32 v59, v145
	v_mov_b32_e32 v60, v145
	v_mov_b32_e32 v61, v145
	v_mov_b32_e32 v62, v145
	v_mov_b32_e32 v63, v145
	v_mov_b32_e32 v64, v145
	v_mov_b32_e32 v65, v145
	v_mov_b32_e32 v66, v145
	v_mov_b32_e32 v67, v145
	v_mov_b32_e32 v68, v145
	v_mov_b32_e32 v69, v145
	v_mov_b32_e32 v70, v145
	v_mov_b32_e32 v71, v145
	v_mov_b32_e32 v72, v145
	v_mov_b32_e32 v73, v145
	v_mov_b32_e32 v74, v145
	v_mov_b32_e32 v75, v145
	v_mov_b32_e32 v76, v145
	v_mov_b32_e32 v77, v145
	v_mov_b32_e32 v78, v145
	v_mov_b32_e32 v79, v145
	v_mov_b32_e32 v80, v145
	v_mov_b32_e32 v81, v145
	v_mov_b32_e32 v82, v145
	v_mov_b32_e32 v83, v145
	v_mov_b32_e32 v84, v145
	v_mov_b32_e32 v85, v145
	v_mov_b32_e32 v86, v145
	v_mov_b32_e32 v87, v145
	v_mov_b32_e32 v88, v145
	v_mov_b32_e32 v89, v145
	v_mov_b32_e32 v90, v145
	v_mov_b32_e32 v91, v145
	v_mov_b32_e32 v92, v145
	v_mov_b32_e32 v93, v145
	v_mov_b32_e32 v94, v145
	v_mov_b32_e32 v95, v145
	v_mov_b32_e32 v96, v145
	v_mov_b32_e32 v97, v145
	v_mov_b32_e32 v98, v145
	v_mov_b32_e32 v99, v145
	v_mov_b32_e32 v100, v145
	v_mov_b32_e32 v101, v145
	v_mov_b32_e32 v102, v145
	v_mov_b32_e32 v103, v145
	v_mov_b32_e32 v104, v145
	v_mov_b32_e32 v105, v145
	v_mov_b32_e32 v106, v145
	v_mov_b32_e32 v107, v145
	v_mov_b32_e32 v108, v145
	v_mov_b32_e32 v109, v145
	v_mov_b32_e32 v110, v145
	v_mov_b32_e32 v111, v145
	v_mov_b32_e32 v112, v145
	v_mov_b32_e32 v113, v145
	v_mov_b32_e32 v114, v145
	v_mov_b32_e32 v115, v145
	v_mov_b32_e32 v116, v145
	v_mov_b32_e32 v117, v145
	v_mov_b32_e32 v118, v145
	v_mov_b32_e32 v119, v145
	v_mov_b32_e32 v120, v145
	v_mov_b32_e32 v121, v145
	v_mov_b32_e32 v122, v145
	v_mov_b32_e32 v123, v145
	v_mov_b32_e32 v124, v145
	v_mov_b32_e32 v125, v145
	v_mov_b32_e32 v126, v145
	v_mov_b32_e32 v127, v145
	s_sub_u32 s76, s43, s35
	v_lshrrev_b32_e32 v196, 5, v179
	v_add_u32_e32 v196, -1, v196
	v_and_b32_e32 v196, s76, v196
	v_and_b32_e32 v194, 31, v179
	v_lshl_add_u32 v194, v194, 11, v196
	s_cmp_eq_u32 s80, 1
	s_cbranch_scc0 .Lpfp_L1
	s_mov_b32 s80, 0
	s_waitcnt vmcnt(16)
	s_barrier
	s_branch .Lkin_L1

.LBB0_728:
	s_andn2_b64 vcc, exec, s[6:7]
	s_cbranch_vccnz .LBB0_725
	s_add_i32 s50, s46, 0x10000
	s_and_b32 s6, s50, 0x10000
	s_add_i32 s51, s6, s26
	s_add_i32 s52, s51, 0x8000
	s_add_u32 s82, s4, s81
	s_addk_i32 s82, 0x80
	s_and_b32 s82, s82, 0x7ff
	s_mov_b32 s83, 0
	s_add_u32 s6, s43, s82
	s_addc_u32 s7, s44, s83
	s_mov_b32 m0, s51
	global_load_lds_dwordx4 v177, s[6:7]
	s_add_u32 s6, s41, s82
	s_addc_u32 s7, s42, s83
	s_add_i32 s53, s51, 0x400
	s_mov_b32 m0, s53
	global_load_lds_dwordx4 v185, s[6:7]
	s_add_u32 s6, s39, s82
	s_addc_u32 s7, s40, s83
	s_add_i32 s53, s51, 0x800
	s_mov_b32 m0, s53
	global_load_lds_dwordx4 v177, s[6:7]
	s_add_u32 s6, s37, s82
	s_addc_u32 s7, s38, s83
	s_add_i32 s53, s51, 0xc00
	s_mov_b32 m0, s53
	global_load_lds_dwordx4 v185, s[6:7]
	s_add_u32 s6, s35, s82
	s_addc_u32 s7, s36, s83
	s_mov_b32 m0, s52
	global_load_lds_dwordx4 v177, s[6:7]
	s_add_u32 s6, s31, s82
	s_addc_u32 s7, s34, s83
	s_add_i32 s52, s51, 0x8400
	s_mov_b32 m0, s52
	global_load_lds_dwordx4 v185, s[6:7]
	s_add_u32 s6, s29, s82
	s_addc_u32 s7, s30, s83
	s_add_i32 s52, s51, 0x8800
	s_mov_b32 m0, s52
	global_load_lds_dwordx4 v177, s[6:7]
	s_add_u32 s6, s27, s82
	s_addc_u32 s7, s28, s83
	s_add_i32 s51, s51, 0x8c00
	s_mov_b32 m0, s51
	global_load_lds_dwordx4 v185, s[6:7]
	s_add_u32 s76, s4, s81
	s_addk_i32 s76, 0x200
	s_and_b32 s76, s76, 0x7ff
	s_add_u32 s78, s35, s76
	s_addc_u32 s79, s36, 0
	global_load_dword v195, v194, s[78:79]
	s_branch .LBB0_725

.Lpe_notv_L1:
	s_cmp_ge_u32 s25, 9
	s_cbranch_scc1 .Lpe_gates_L1
	s_lshr_b32 s34, s25, 1
	s_cmp_ge_u32 s25, 6
	s_cselect_b32 s35, 1, 0
	s_sub_u32 s34, s34, s35
	s_lshl_b32 s35, s98, 2
	s_add_u32 s35, s35, s34
	s_lshl_b32 s35, s35, 8
	v_readlane_b32 s82, v254, 14
	v_readlane_b32 s83, v254, 15
	s_add_u32 s82, s82, s35
	s_addc_u32 s83, s83, 0
	global_load_dwordx4 v[198:201], v146, s[82:83] offset:0
	global_load_dwordx4 v[202:205], v146, s[82:83] offset:32
	global_load_dwordx4 v[206:209], v146, s[82:83] offset:64
	global_load_dwordx4 v[210:213], v146, s[82:83] offset:96
	global_load_dwordx4 v[214:217], v146, s[82:83] offset:128
	global_load_dwordx4 v[218:221], v146, s[82:83] offset:160
	global_load_dwordx4 v[222:225], v146, s[82:83] offset:192
	global_load_dwordx4 v[226:229], v146, s[82:83] offset:224
	s_and_b32 s35, s34, 1
	s_cmp_eq_u32 s35, 0
	s_cselect_b32 s36, 0x3e000000, 1.0
	s_and_b32 s35, s29, 0x7ff
	s_lshl_b32 s35, s35, 7
	s_add_u32 s96, s72, 0x1ada0000
	s_addc_u32 s97, s73, 0
	s_add_u32 s96, s96, s35
	s_addc_u32 s97, s97, 0
	s_add_u32 s100, s96, 0x40000
	s_addc_u32 s101, s97, 0
	s_cmp_ge_u32 s34, 2
	s_cselect_b32 s37, 1, 0
	s_waitcnt vmcnt(8)
	v_lshlrev_b32_e32 v180, 7, v197
	v_add_u32_e32 v180, v180, v146
	v_mov_b32_e32 v197, 0x358637bd
	v_pk_add_f32 v[128:129], v[128:129], v[130:131]
	v_pk_add_f32 v[132:133], v[132:133], v[134:135]
	v_pk_add_f32 v[136:137], v[136:137], v[138:139]
	v_pk_add_f32 v[140:141], v[140:141], v[142:143]
	v_pk_add_f32 v[164:165], v[164:165], v[166:167]
	v_pk_add_f32 v[168:169], v[168:169], v[170:171]
	v_pk_add_f32 v[246:247], v[246:247], v[248:249]
	v_pk_add_f32 v[250:251], v[250:251], v[252:253]
	v_pk_add_f32 v[128:129], v[128:129], v[132:133]
	v_pk_add_f32 v[136:137], v[136:137], v[140:141]
	v_pk_add_f32 v[164:165], v[164:165], v[168:169]
	v_pk_add_f32 v[246:247], v[246:247], v[250:251]
	v_add_f32_e32 v128, v128, v129
	v_add_f32_e32 v136, v136, v137
	v_add_f32_e32 v164, v164, v165
	v_add_f32_e32 v246, v246, v247
	v_fmamk_f32 v128, v128, 0x3a800000, v197
	v_fmamk_f32 v136, v136, 0x3a800000, v197
	v_fmamk_f32 v164, v164, 0x3a800000, v197
	v_fmamk_f32 v246, v246, 0x3a800000, v197
	v_rsq_f32_e32 v172, v128
	v_rsq_f32_e32 v173, v136
	v_rsq_f32_e32 v174, v164
	v_rsq_f32_e32 v175, v246
	s_nop 0
	s_add_u32 s76, s99, s90
	s_cmp_lt_u32 s76, 0x440
	s_cselect_b32 s80, 1, 0
	s_cselect_b32 s83, 0x200000, 0
	s_lshl_b32 s76, s24, 19
	s_lshl_b32 s77, s26, 16
	s_add_u32 s76, s76, s77
	s_and_b32 s77, s24, 7
	s_lshl_b32 s77, s77, 8
	s_add_u32 s76, s76, s77
	s_add_u32 s78, s72, 0xa120000
	s_addc_u32 s79, s73, 0
	s_add_u32 s78, s78, s76
	s_addc_u32 s79, s79, 0
	s_lshl_b32 s76, s25, 19
	s_add_u32 s76, s76, s83
	s_add_u32 s76, s76, s77
	s_lshl_b32 s77, s26, 16
	s_add_u32 s76, s76, s77
	s_add_u32 s82, s72, 0x880000
	s_addc_u32 s83, s73, 0
	s_add_u32 s82, s82, s76
	s_addc_u32 s83, s83, 0
	s_lshl_b32 s76, s26, 12
	s_mov_b32 m0, s76
	s_nop 0
	global_load_lds_dwordx4 v177, s[78:79]
	s_add_u32 s78, s78, 0x4000
	s_addc_u32 s79, s79, 0
	s_add_u32 s76, s76, 0x400
	s_mov_b32 m0, s76
	s_nop 0
	global_load_lds_dwordx4 v185, s[78:79]
	s_add_u32 s78, s78, 0x4000
	s_addc_u32 s79, s79, 0
	s_add_u32 s76, s76, 0x400
	s_mov_b32 m0, s76
	s_nop 0
	global_load_lds_dwordx4 v177, s[78:79]
	s_add_u32 s78, s78, 0x4000
	s_addc_u32 s79, s79, 0
	s_add_u32 s76, s76, 0x400
	s_mov_b32 m0, s76
	s_nop 0
	global_load_lds_dwordx4 v185, s[78:79]
	s_add_u32 s78, s78, 0x4000
	s_addc_u32 s79, s79, 0
	s_add_u32 s76, s76, 0x400
	s_add_u32 s76, s76, 0x7000
	s_mov_b32 m0, s76
	s_nop 0
	global_load_lds_dwordx4 v177, s[82:83]
	s_add_u32 s82, s82, 0x4000
	s_addc_u32 s83, s83, 0
	s_add_u32 s76, s76, 0x400
	s_mov_b32 m0, s76
	s_nop 0
	global_load_lds_dwordx4 v185, s[82:83]
	s_add_u32 s82, s82, 0x4000
	s_addc_u32 s83, s83, 0
	s_add_u32 s76, s76, 0x400
	s_mov_b32 m0, s76
	s_nop 0
	global_load_lds_dwordx4 v177, s[82:83]
	s_add_u32 s82, s82, 0x4000
	s_addc_u32 s83, s83, 0
	s_add_u32 s76, s76, 0x400
	s_mov_b32 m0, s76
	s_nop 0
	global_load_lds_dwordx4 v185, s[82:83]
	s_add_u32 s82, s82, 0x4000
	s_addc_u32 s83, s83, 0
	s_add_u32 s76, s76, 0x400
	s_and_b32 s77, s24, 7
	s_lshl_b32 s77, s77, 8
	s_add_u32 s76, s77, 0x10000
	s_sub_u32 s78, s78, s76
	s_subb_u32 s79, s79, 0
	s_sub_u32 s82, s82, s76
	s_subb_u32 s83, s83, 0
	s_sub_u32 s76, s78, s82
	v_lshrrev_b32_e32 v196, 5, v179
	v_add_u32_e32 v196, -1, v196
	v_and_b32_e32 v196, s76, v196
	v_and_b32_e32 v194, 31, v179
	v_lshl_add_u32 v194, v194, 11, v196
	s_add_u32 s76, s77, 0x80
	s_and_b32 s76, s76, 0x7ff
	s_add_u32 s78, s82, s76
	s_addc_u32 s79, s83, 0
	global_load_dword v195, v194, s[78:79]
	s_add_u32 s76, s77, 0x100
	s_and_b32 s76, s76, 0x7ff
	s_add_u32 s78, s82, s76
	s_addc_u32 s79, s83, 0
	global_load_dword v195, v194, s[78:79]
	s_add_u32 s76, s77, 0x180
	s_and_b32 s76, s76, 0x7ff
	s_add_u32 s78, s82, s76
	s_addc_u32 s79, s83, 0
	global_load_dword v195, v194, s[78:79]
	s_add_u32 s76, s77, 0x200
	s_and_b32 s76, s76, 0x7ff
	s_add_u32 s78, s82, s76
	s_addc_u32 s79, s83, 0
	global_load_dword v195, v194, s[78:79]
	s_cmp_eq_u32 s37, 0
	s_cbranch_scc1 .Lpe_norope_ld_L1
	global_load_dwordx4 v[230:233], v180, s[96:97] offset:0
	global_load_dwordx4 v[234:237], v180, s[96:97] offset:32
	global_load_dwordx4 v[238:241], v180, s[96:97] offset:64
	global_load_dwordx4 v[242:245], v180, s[96:97] offset:96
	global_load_dwordx4 v[148:151], v180, s[100:101] offset:0
	global_load_dwordx4 v[152:155], v180, s[100:101] offset:32
	global_load_dwordx4 v[156:159], v180, s[100:101] offset:64
	global_load_dwordx4 v[160:163], v180, s[100:101] offset:96

.Lpe_gates_L1:
	s_lshl_b32 s35, s98, 11
	s_add_u32 s35, s35, s30
	s_sub_u32 s35, s35, 0x900
	s_lshl_b32 s35, s35, 2
	v_readlane_b32 s82, v254, 12
	v_readlane_b32 s83, v254, 13
	s_add_u32 s82, s82, s35
	s_addc_u32 s83, s83, 0
	global_load_dwordx4 v[198:201], v146, s[82:83] offset:0
	global_load_dwordx4 v[202:205], v146, s[82:83] offset:32
	global_load_dwordx4 v[206:209], v146, s[82:83] offset:64
	global_load_dwordx4 v[210:213], v146, s[82:83] offset:96
	global_load_dwordx4 v[214:217], v146, s[82:83] offset:128
	global_load_dwordx4 v[218:221], v146, s[82:83] offset:160
	global_load_dwordx4 v[222:225], v146, s[82:83] offset:192
	global_load_dwordx4 v[226:229], v146, s[82:83] offset:224
	s_waitcnt vmcnt(8)
	v_mov_b32_e32 v197, 0x358637bd
	v_pk_add_f32 v[128:129], v[128:129], v[130:131]
	v_pk_add_f32 v[132:133], v[132:133], v[134:135]
	v_pk_add_f32 v[136:137], v[136:137], v[138:139]
	v_pk_add_f32 v[140:141], v[140:141], v[142:143]
	v_pk_add_f32 v[164:165], v[164:165], v[166:167]
	v_pk_add_f32 v[168:169], v[168:169], v[170:171]
	v_pk_add_f32 v[246:247], v[246:247], v[248:249]
	v_pk_add_f32 v[250:251], v[250:251], v[252:253]
	v_pk_add_f32 v[128:129], v[128:129], v[132:133]
	v_pk_add_f32 v[136:137], v[136:137], v[140:141]
	v_pk_add_f32 v[164:165], v[164:165], v[168:169]
	v_pk_add_f32 v[246:247], v[246:247], v[250:251]
	v_add_f32_e32 v128, v128, v129
	v_add_f32_e32 v136, v136, v137
	v_add_f32_e32 v164, v164, v165
	v_add_f32_e32 v246, v246, v247
	v_fmamk_f32 v128, v128, 0x3a800000, v197
	v_fmamk_f32 v136, v136, 0x3a800000, v197
	v_fmamk_f32 v164, v164, 0x3a800000, v197
	v_fmamk_f32 v246, v246, 0x3a800000, v197
	v_rsq_f32_e32 v172, v128
	v_rsq_f32_e32 v173, v136
	v_rsq_f32_e32 v174, v164
	v_rsq_f32_e32 v175, v246
	s_nop 0
	s_add_u32 s76, s99, s90
	s_cmp_lt_u32 s76, 0x440
	s_cselect_b32 s80, 1, 0
	s_cselect_b32 s83, 0x200000, 0
	s_lshl_b32 s76, s24, 19
	s_lshl_b32 s77, s26, 16
	s_add_u32 s76, s76, s77
	s_and_b32 s77, s24, 7
	s_lshl_b32 s77, s77, 8
	s_add_u32 s76, s76, s77
	s_add_u32 s78, s72, 0xa120000
	s_addc_u32 s79, s73, 0
	s_add_u32 s78, s78, s76
	s_addc_u32 s79, s79, 0
	s_lshl_b32 s76, s25, 19
	s_add_u32 s76, s76, s83
	s_add_u32 s76, s76, s77
	s_lshl_b32 s77, s26, 16
	s_add_u32 s76, s76, s77
	s_add_u32 s82, s72, 0x880000
	s_addc_u32 s83, s73, 0
	s_add_u32 s82, s82, s76
	s_addc_u32 s83, s83, 0
	s_lshl_b32 s76, s26, 12
	s_mov_b32 m0, s76
	s_nop 0
	global_load_lds_dwordx4 v177, s[78:79]
	s_add_u32 s78, s78, 0x4000
	s_addc_u32 s79, s79, 0
	s_add_u32 s76, s76, 0x400
	s_mov_b32 m0, s76
	s_nop 0
	global_load_lds_dwordx4 v185, s[78:79]
	s_add_u32 s78, s78, 0x4000
	s_addc_u32 s79, s79, 0
	s_add_u32 s76, s76, 0x400
	s_mov_b32 m0, s76
	s_nop 0
	global_load_lds_dwordx4 v177, s[78:79]
	s_add_u32 s78, s78, 0x4000
	s_addc_u32 s79, s79, 0
	s_add_u32 s76, s76, 0x400
	s_mov_b32 m0, s76
	s_nop 0
	global_load_lds_dwordx4 v185, s[78:79]
	s_add_u32 s78, s78, 0x4000
	s_addc_u32 s79, s79, 0
	s_add_u32 s76, s76, 0x400
	s_add_u32 s76, s76, 0x7000
	s_mov_b32 m0, s76
	s_nop 0
	global_load_lds_dwordx4 v177, s[82:83]
	s_add_u32 s82, s82, 0x4000
	s_addc_u32 s83, s83, 0
	s_add_u32 s76, s76, 0x400
	s_mov_b32 m0, s76
	s_nop 0
	global_load_lds_dwordx4 v185, s[82:83]
	s_add_u32 s82, s82, 0x4000
	s_addc_u32 s83, s83, 0
	s_add_u32 s76, s76, 0x400
	s_mov_b32 m0, s76
	s_nop 0
	global_load_lds_dwordx4 v177, s[82:83]
	s_add_u32 s82, s82, 0x4000
	s_addc_u32 s83, s83, 0
	s_add_u32 s76, s76, 0x400
	s_mov_b32 m0, s76
	s_nop 0
	global_load_lds_dwordx4 v185, s[82:83]
	s_add_u32 s82, s82, 0x4000
	s_addc_u32 s83, s83, 0
	s_add_u32 s76, s76, 0x400
	s_and_b32 s77, s24, 7
	s_lshl_b32 s77, s77, 8
	s_add_u32 s76, s77, 0x10000
	s_sub_u32 s78, s78, s76
	s_subb_u32 s79, s79, 0
	s_sub_u32 s82, s82, s76
	s_subb_u32 s83, s83, 0
	s_sub_u32 s76, s78, s82
	v_lshrrev_b32_e32 v196, 5, v179
	v_add_u32_e32 v196, -1, v196
	v_and_b32_e32 v196, s76, v196
	v_and_b32_e32 v194, 31, v179
	v_lshl_add_u32 v194, v194, 11, v196
	s_add_u32 s76, s77, 0x80
	s_and_b32 s76, s76, 0x7ff
	s_add_u32 s78, s82, s76
	s_addc_u32 s79, s83, 0
	global_load_dword v195, v194, s[78:79]
	s_add_u32 s76, s77, 0x100
	s_and_b32 s76, s76, 0x7ff
	s_add_u32 s78, s82, s76
	s_addc_u32 s79, s83, 0
	global_load_dword v195, v194, s[78:79]
	s_add_u32 s76, s77, 0x180
	s_and_b32 s76, s76, 0x7ff
	s_add_u32 s78, s82, s76
	s_addc_u32 s79, s83, 0
	global_load_dword v195, v194, s[78:79]
	s_add_u32 s76, s77, 0x200
	s_and_b32 s76, s76, 0x7ff
	s_add_u32 s78, s82, s76
	s_addc_u32 s79, s83, 0
	global_load_dword v195, v194, s[78:79]
	v_mul_f32_e32 v172, 0xbfb8aa3b, v172
	v_mul_f32_e32 v173, 0xbfb8aa3b, v173
	v_mul_f32_e32 v174, 0xbfb8aa3b, v174
	v_mul_f32_e32 v175, 0xbfb8aa3b, v175
	s_waitcnt vmcnt(12)
	v_mul_f32_e32 v198, 0xbfb8aa3b, v198
	v_mul_f32_e32 v199, 0xbfb8aa3b, v199
	v_mul_f32_e32 v200, 0xbfb8aa3b, v200
	v_mul_f32_e32 v201, 0xbfb8aa3b, v201
	v_mul_f32_e32 v202, 0xbfb8aa3b, v202
	v_mul_f32_e32 v203, 0xbfb8aa3b, v203
	v_mul_f32_e32 v204, 0xbfb8aa3b, v204
	v_mul_f32_e32 v205, 0xbfb8aa3b, v205
	v_mul_f32_e32 v206, 0xbfb8aa3b, v206
	v_mul_f32_e32 v207, 0xbfb8aa3b, v207
	v_mul_f32_e32 v208, 0xbfb8aa3b, v208
	v_mul_f32_e32 v209, 0xbfb8aa3b, v209
	v_mul_f32_e32 v210, 0xbfb8aa3b, v210
	v_mul_f32_e32 v211, 0xbfb8aa3b, v211
	v_mul_f32_e32 v212, 0xbfb8aa3b, v212
	v_mul_f32_e32 v213, 0xbfb8aa3b, v213
	v_mul_f32_e32 v214, 0xbfb8aa3b, v214
	v_mul_f32_e32 v215, 0xbfb8aa3b, v215
	v_mul_f32_e32 v216, 0xbfb8aa3b, v216
	v_mul_f32_e32 v217, 0xbfb8aa3b, v217
	v_mul_f32_e32 v218, 0xbfb8aa3b, v218
	v_mul_f32_e32 v219, 0xbfb8aa3b, v219
	v_mul_f32_e32 v220, 0xbfb8aa3b, v220
	v_mul_f32_e32 v221, 0xbfb8aa3b, v221
	v_mul_f32_e32 v222, 0xbfb8aa3b, v222
	v_mul_f32_e32 v223, 0xbfb8aa3b, v223
	v_mul_f32_e32 v224, 0xbfb8aa3b, v224
	v_mul_f32_e32 v225, 0xbfb8aa3b, v225
	v_mul_f32_e32 v226, 0xbfb8aa3b, v226
	v_mul_f32_e32 v227, 0xbfb8aa3b, v227
	v_mul_f32_e32 v228, 0xbfb8aa3b, v228
	v_mul_f32_e32 v229, 0xbfb8aa3b, v229
	v_pk_fma_f32 v[0:1], v[0:1], v[172:173], v[198:199] op_sel_hi:[1,0,1]
	v_pk_fma_f32 v[2:3], v[2:3], v[172:173], v[200:201] op_sel_hi:[1,0,1]
	v_pk_fma_f32 v[4:5], v[4:5], v[172:173], v[202:203] op_sel_hi:[1,0,1]
	v_pk_fma_f32 v[6:7], v[6:7], v[172:173], v[204:205] op_sel_hi:[1,0,1]
	v_pk_fma_f32 v[8:9], v[8:9], v[172:173], v[206:207] op_sel_hi:[1,0,1]
	v_pk_fma_f32 v[10:11], v[10:11], v[172:173], v[208:209] op_sel_hi:[1,0,1]
	v_pk_fma_f32 v[12:13], v[12:13], v[172:173], v[210:211] op_sel_hi:[1,0,1]
	v_pk_fma_f32 v[14:15], v[14:15], v[172:173], v[212:213] op_sel_hi:[1,0,1]
	v_pk_fma_f32 v[16:17], v[16:17], v[172:173], v[214:215] op_sel_hi:[1,0,1]
	v_pk_fma_f32 v[18:19], v[18:19], v[172:173], v[216:217] op_sel_hi:[1,0,1]
	v_pk_fma_f32 v[20:21], v[20:21], v[172:173], v[218:219] op_sel_hi:[1,0,1]
	v_pk_fma_f32 v[22:23], v[22:23], v[172:173], v[220:221] op_sel_hi:[1,0,1]
	v_pk_fma_f32 v[24:25], v[24:25], v[172:173], v[222:223] op_sel_hi:[1,0,1]
	v_pk_fma_f32 v[26:27], v[26:27], v[172:173], v[224:225] op_sel_hi:[1,0,1]
	v_pk_fma_f32 v[28:29], v[28:29], v[172:173], v[226:227] op_sel_hi:[1,0,1]
	v_pk_fma_f32 v[30:31], v[30:31], v[172:173], v[228:229] op_sel_hi:[1,0,1]
	v_exp_f32_e32 v0, v0
	v_exp_f32_e32 v1, v1
	v_exp_f32_e32 v2, v2
	v_exp_f32_e32 v3, v3
	v_exp_f32_e32 v4, v4
	v_exp_f32_e32 v5, v5
	v_exp_f32_e32 v6, v6
	v_exp_f32_e32 v7, v7
	v_exp_f32_e32 v8, v8
	v_exp_f32_e32 v9, v9
	v_exp_f32_e32 v10, v10
	v_exp_f32_e32 v11, v11
	v_exp_f32_e32 v12, v12
	v_exp_f32_e32 v13, v13
	v_exp_f32_e32 v14, v14
	v_exp_f32_e32 v15, v15
	v_exp_f32_e32 v16, v16
	v_exp_f32_e32 v17, v17
	v_exp_f32_e32 v18, v18
	v_exp_f32_e32 v19, v19
	v_exp_f32_e32 v20, v20
	v_exp_f32_e32 v21, v21
	v_exp_f32_e32 v22, v22
	v_exp_f32_e32 v23, v23
	v_exp_f32_e32 v24, v24
	v_exp_f32_e32 v25, v25
	v_exp_f32_e32 v26, v26
	v_exp_f32_e32 v27, v27
	v_exp_f32_e32 v28, v28
	v_exp_f32_e32 v29, v29
	v_exp_f32_e32 v30, v30
	v_exp_f32_e32 v31, v31
	v_pk_add_f32 v[0:1], v[0:1], 1.0 op_sel_hi:[1,0]
	v_pk_add_f32 v[2:3], v[2:3], 1.0 op_sel_hi:[1,0]
	v_pk_add_f32 v[4:5], v[4:5], 1.0 op_sel_hi:[1,0]
	v_pk_add_f32 v[6:7], v[6:7], 1.0 op_sel_hi:[1,0]
	v_pk_add_f32 v[8:9], v[8:9], 1.0 op_sel_hi:[1,0]
	v_pk_add_f32 v[10:11], v[10:11], 1.0 op_sel_hi:[1,0]
	v_pk_add_f32 v[12:13], v[12:13], 1.0 op_sel_hi:[1,0]
	v_pk_add_f32 v[14:15], v[14:15], 1.0 op_sel_hi:[1,0]
	v_pk_add_f32 v[16:17], v[16:17], 1.0 op_sel_hi:[1,0]
	v_pk_add_f32 v[18:19], v[18:19], 1.0 op_sel_hi:[1,0]
	v_pk_add_f32 v[20:21], v[20:21], 1.0 op_sel_hi:[1,0]
	v_pk_add_f32 v[22:23], v[22:23], 1.0 op_sel_hi:[1,0]
	v_pk_add_f32 v[24:25], v[24:25], 1.0 op_sel_hi:[1,0]
	v_pk_add_f32 v[26:27], v[26:27], 1.0 op_sel_hi:[1,0]
	v_pk_add_f32 v[28:29], v[28:29], 1.0 op_sel_hi:[1,0]
	v_pk_add_f32 v[30:31], v[30:31], 1.0 op_sel_hi:[1,0]
	v_rcp_f32_e32 v0, v0
	v_rcp_f32_e32 v1, v1
	v_rcp_f32_e32 v2, v2
	v_rcp_f32_e32 v3, v3
	v_rcp_f32_e32 v4, v4
	v_rcp_f32_e32 v5, v5
	v_rcp_f32_e32 v6, v6
	v_rcp_f32_e32 v7, v7
	v_rcp_f32_e32 v8, v8
	v_rcp_f32_e32 v9, v9
	v_rcp_f32_e32 v10, v10
	v_rcp_f32_e32 v11, v11
	v_rcp_f32_e32 v12, v12
	v_rcp_f32_e32 v13, v13
	v_rcp_f32_e32 v14, v14
	v_rcp_f32_e32 v15, v15
	v_rcp_f32_e32 v16, v16
	v_rcp_f32_e32 v17, v17
	v_rcp_f32_e32 v18, v18
	v_rcp_f32_e32 v19, v19
	v_rcp_f32_e32 v20, v20
	v_rcp_f32_e32 v21, v21
	v_rcp_f32_e32 v22, v22
	v_rcp_f32_e32 v23, v23
	v_rcp_f32_e32 v24, v24
	v_rcp_f32_e32 v25, v25
	v_rcp_f32_e32 v26, v26
	v_rcp_f32_e32 v27, v27
	v_rcp_f32_e32 v28, v28
	v_rcp_f32_e32 v29, v29
	v_rcp_f32_e32 v30, v30
	v_rcp_f32_e32 v31, v31
	s_nop 0
	v_cvt_pk_bf16_f32 v0, v0, v1
	v_cvt_pk_bf16_f32 v1, v2, v3
	v_cvt_pk_bf16_f32 v2, v4, v5
	v_cvt_pk_bf16_f32 v3, v6, v7
	v_cvt_pk_bf16_f32 v4, v8, v9
	v_cvt_pk_bf16_f32 v5, v10, v11
	v_cvt_pk_bf16_f32 v6, v12, v13
	v_cvt_pk_bf16_f32 v7, v14, v15
	v_cvt_pk_bf16_f32 v16, v16, v17
	v_cvt_pk_bf16_f32 v17, v18, v19
	v_cvt_pk_bf16_f32 v18, v20, v21
	v_cvt_pk_bf16_f32 v19, v22, v23
	v_cvt_pk_bf16_f32 v20, v24, v25
	v_cvt_pk_bf16_f32 v21, v26, v27
	v_cvt_pk_bf16_f32 v22, v28, v29
	v_cvt_pk_bf16_f32 v23, v30, v31
	v_permlane32_swap_b32_e32 v0, v2
	v_permlane32_swap_b32_e32 v1, v3
	v_permlane32_swap_b32_e32 v4, v6
	v_permlane32_swap_b32_e32 v5, v7
	v_permlane32_swap_b32_e32 v16, v18
	v_permlane32_swap_b32_e32 v17, v19
	v_permlane32_swap_b32_e32 v20, v22
	v_permlane32_swap_b32_e32 v21, v23
	global_store_dwordx4 v181, v[0:3], s[74:75] offset:0
	global_store_dwordx4 v181, v[4:7], s[74:75] offset:32
	global_store_dwordx4 v181, v[16:19], s[74:75] offset:64
	global_store_dwordx4 v181, v[20:23], s[74:75] offset:96
	s_add_u32 s74, s74, 0x44000
	s_addc_u32 s75, s75, 0
	v_pk_fma_f32 v[32:33], v[32:33], v[172:173], v[198:199] op_sel:[0,1,0] op_sel_hi:[1,1,1]
	v_pk_fma_f32 v[34:35], v[34:35], v[172:173], v[200:201] op_sel:[0,1,0] op_sel_hi:[1,1,1]
	v_pk_fma_f32 v[36:37], v[36:37], v[172:173], v[202:203] op_sel:[0,1,0] op_sel_hi:[1,1,1]
	v_pk_fma_f32 v[38:39], v[38:39], v[172:173], v[204:205] op_sel:[0,1,0] op_sel_hi:[1,1,1]
	v_pk_fma_f32 v[40:41], v[40:41], v[172:173], v[206:207] op_sel:[0,1,0] op_sel_hi:[1,1,1]
	v_pk_fma_f32 v[42:43], v[42:43], v[172:173], v[208:209] op_sel:[0,1,0] op_sel_hi:[1,1,1]
	v_pk_fma_f32 v[44:45], v[44:45], v[172:173], v[210:211] op_sel:[0,1,0] op_sel_hi:[1,1,1]
	v_pk_fma_f32 v[46:47], v[46:47], v[172:173], v[212:213] op_sel:[0,1,0] op_sel_hi:[1,1,1]
	v_pk_fma_f32 v[48:49], v[48:49], v[172:173], v[214:215] op_sel:[0,1,0] op_sel_hi:[1,1,1]
	v_pk_fma_f32 v[50:51], v[50:51], v[172:173], v[216:217] op_sel:[0,1,0] op_sel_hi:[1,1,1]
	v_pk_fma_f32 v[52:53], v[52:53], v[172:173], v[218:219] op_sel:[0,1,0] op_sel_hi:[1,1,1]
	v_pk_fma_f32 v[54:55], v[54:55], v[172:173], v[220:221] op_sel:[0,1,0] op_sel_hi:[1,1,1]
	v_pk_fma_f32 v[56:57], v[56:57], v[172:173], v[222:223] op_sel:[0,1,0] op_sel_hi:[1,1,1]
	v_pk_fma_f32 v[58:59], v[58:59], v[172:173], v[224:225] op_sel:[0,1,0] op_sel_hi:[1,1,1]
	v_pk_fma_f32 v[60:61], v[60:61], v[172:173], v[226:227] op_sel:[0,1,0] op_sel_hi:[1,1,1]
	v_pk_fma_f32 v[62:63], v[62:63], v[172:173], v[228:229] op_sel:[0,1,0] op_sel_hi:[1,1,1]
	v_exp_f32_e32 v32, v32
	v_exp_f32_e32 v33, v33
	v_exp_f32_e32 v34, v34
	v_exp_f32_e32 v35, v35
	v_exp_f32_e32 v36, v36
	v_exp_f32_e32 v37, v37
	v_exp_f32_e32 v38, v38
	v_exp_f32_e32 v39, v39
	v_exp_f32_e32 v40, v40
	v_exp_f32_e32 v41, v41
	v_exp_f32_e32 v42, v42
	v_exp_f32_e32 v43, v43
	v_exp_f32_e32 v44, v44
	v_exp_f32_e32 v45, v45
	v_exp_f32_e32 v46, v46
	v_exp_f32_e32 v47, v47
	v_exp_f32_e32 v48, v48
	v_exp_f32_e32 v49, v49
	v_exp_f32_e32 v50, v50
	v_exp_f32_e32 v51, v51
	v_exp_f32_e32 v52, v52
	v_exp_f32_e32 v53, v53
	v_exp_f32_e32 v54, v54
	v_exp_f32_e32 v55, v55
	v_exp_f32_e32 v56, v56
	v_exp_f32_e32 v57, v57
	v_exp_f32_e32 v58, v58
	v_exp_f32_e32 v59, v59
	v_exp_f32_e32 v60, v60
	v_exp_f32_e32 v61, v61
	v_exp_f32_e32 v62, v62
	v_exp_f32_e32 v63, v63
	v_pk_add_f32 v[32:33], v[32:33], 1.0 op_sel_hi:[1,0]
	v_pk_add_f32 v[34:35], v[34:35], 1.0 op_sel_hi:[1,0]
	v_pk_add_f32 v[36:37], v[36:37], 1.0 op_sel_hi:[1,0]
	v_pk_add_f32 v[38:39], v[38:39], 1.0 op_sel_hi:[1,0]
	v_pk_add_f32 v[40:41], v[40:41], 1.0 op_sel_hi:[1,0]
	v_pk_add_f32 v[42:43], v[42:43], 1.0 op_sel_hi:[1,0]
	v_pk_add_f32 v[44:45], v[44:45], 1.0 op_sel_hi:[1,0]
	v_pk_add_f32 v[46:47], v[46:47], 1.0 op_sel_hi:[1,0]
	v_pk_add_f32 v[48:49], v[48:49], 1.0 op_sel_hi:[1,0]
	v_pk_add_f32 v[50:51], v[50:51], 1.0 op_sel_hi:[1,0]
	v_pk_add_f32 v[52:53], v[52:53], 1.0 op_sel_hi:[1,0]
	v_pk_add_f32 v[54:55], v[54:55], 1.0 op_sel_hi:[1,0]
	v_pk_add_f32 v[56:57], v[56:57], 1.0 op_sel_hi:[1,0]
	v_pk_add_f32 v[58:59], v[58:59], 1.0 op_sel_hi:[1,0]
	v_pk_add_f32 v[60:61], v[60:61], 1.0 op_sel_hi:[1,0]
	v_pk_add_f32 v[62:63], v[62:63], 1.0 op_sel_hi:[1,0]
	v_rcp_f32_e32 v32, v32
	v_rcp_f32_e32 v33, v33
	v_rcp_f32_e32 v34, v34
	v_rcp_f32_e32 v35, v35
	v_rcp_f32_e32 v36, v36
	v_rcp_f32_e32 v37, v37
	v_rcp_f32_e32 v38, v38
	v_rcp_f32_e32 v39, v39
	v_rcp_f32_e32 v40, v40
	v_rcp_f32_e32 v41, v41
	v_rcp_f32_e32 v42, v42
	v_rcp_f32_e32 v43, v43
	v_rcp_f32_e32 v44, v44
	v_rcp_f32_e32 v45, v45
	v_rcp_f32_e32 v46, v46
	v_rcp_f32_e32 v47, v47
	v_rcp_f32_e32 v48, v48
	v_rcp_f32_e32 v49, v49
	v_rcp_f32_e32 v50, v50
	v_rcp_f32_e32 v51, v51
	v_rcp_f32_e32 v52, v52
	v_rcp_f32_e32 v53, v53
	v_rcp_f32_e32 v54, v54
	v_rcp_f32_e32 v55, v55
	v_rcp_f32_e32 v56, v56
	v_rcp_f32_e32 v57, v57
	v_rcp_f32_e32 v58, v58
	v_rcp_f32_e32 v59, v59
	v_rcp_f32_e32 v60, v60
	v_rcp_f32_e32 v61, v61
	v_rcp_f32_e32 v62, v62
	v_rcp_f32_e32 v63, v63
	s_nop 0
	v_cvt_pk_bf16_f32 v32, v32, v33
	v_cvt_pk_bf16_f32 v33, v34, v35
	v_cvt_pk_bf16_f32 v34, v36, v37
	v_cvt_pk_bf16_f32 v35, v38, v39
	v_cvt_pk_bf16_f32 v36, v40, v41
	v_cvt_pk_bf16_f32 v37, v42, v43
	v_cvt_pk_bf16_f32 v38, v44, v45
	v_cvt_pk_bf16_f32 v39, v46, v47
	v_cvt_pk_bf16_f32 v48, v48, v49
	v_cvt_pk_bf16_f32 v49, v50, v51
	v_cvt_pk_bf16_f32 v50, v52, v53
	v_cvt_pk_bf16_f32 v51, v54, v55
	v_cvt_pk_bf16_f32 v52, v56, v57
	v_cvt_pk_bf16_f32 v53, v58, v59
	v_cvt_pk_bf16_f32 v54, v60, v61
	v_cvt_pk_bf16_f32 v55, v62, v63
	v_permlane32_swap_b32_e32 v32, v34
	v_permlane32_swap_b32_e32 v33, v35
	v_permlane32_swap_b32_e32 v36, v38
	v_permlane32_swap_b32_e32 v37, v39
	v_permlane32_swap_b32_e32 v48, v50
	v_permlane32_swap_b32_e32 v49, v51
	v_permlane32_swap_b32_e32 v52, v54
	v_permlane32_swap_b32_e32 v53, v55
	global_store_dwordx4 v181, v[32:35], s[74:75] offset:0
	global_store_dwordx4 v181, v[36:39], s[74:75] offset:32
	global_store_dwordx4 v181, v[48:51], s[74:75] offset:64
	global_store_dwordx4 v181, v[52:55], s[74:75] offset:96
	s_add_u32 s74, s74, 0x44000
	s_addc_u32 s75, s75, 0
	v_pk_fma_f32 v[64:65], v[64:65], v[174:175], v[198:199] op_sel_hi:[1,0,1]
	v_pk_fma_f32 v[66:67], v[66:67], v[174:175], v[200:201] op_sel_hi:[1,0,1]
	v_pk_fma_f32 v[68:69], v[68:69], v[174:175], v[202:203] op_sel_hi:[1,0,1]
	v_pk_fma_f32 v[70:71], v[70:71], v[174:175], v[204:205] op_sel_hi:[1,0,1]
	v_pk_fma_f32 v[72:73], v[72:73], v[174:175], v[206:207] op_sel_hi:[1,0,1]
	v_pk_fma_f32 v[74:75], v[74:75], v[174:175], v[208:209] op_sel_hi:[1,0,1]
	v_pk_fma_f32 v[76:77], v[76:77], v[174:175], v[210:211] op_sel_hi:[1,0,1]
	v_pk_fma_f32 v[78:79], v[78:79], v[174:175], v[212:213] op_sel_hi:[1,0,1]
	v_pk_fma_f32 v[80:81], v[80:81], v[174:175], v[214:215] op_sel_hi:[1,0,1]
	v_pk_fma_f32 v[82:83], v[82:83], v[174:175], v[216:217] op_sel_hi:[1,0,1]
	v_pk_fma_f32 v[84:85], v[84:85], v[174:175], v[218:219] op_sel_hi:[1,0,1]
	v_pk_fma_f32 v[86:87], v[86:87], v[174:175], v[220:221] op_sel_hi:[1,0,1]
	v_pk_fma_f32 v[88:89], v[88:89], v[174:175], v[222:223] op_sel_hi:[1,0,1]
	v_pk_fma_f32 v[90:91], v[90:91], v[174:175], v[224:225] op_sel_hi:[1,0,1]
	v_pk_fma_f32 v[92:93], v[92:93], v[174:175], v[226:227] op_sel_hi:[1,0,1]
	v_pk_fma_f32 v[94:95], v[94:95], v[174:175], v[228:229] op_sel_hi:[1,0,1]
	v_exp_f32_e32 v64, v64
	v_exp_f32_e32 v65, v65
	v_exp_f32_e32 v66, v66
	v_exp_f32_e32 v67, v67
	v_exp_f32_e32 v68, v68
	v_exp_f32_e32 v69, v69
	v_exp_f32_e32 v70, v70
	v_exp_f32_e32 v71, v71
	v_exp_f32_e32 v72, v72
	v_exp_f32_e32 v73, v73
	v_exp_f32_e32 v74, v74
	v_exp_f32_e32 v75, v75
	v_exp_f32_e32 v76, v76
	v_exp_f32_e32 v77, v77
	v_exp_f32_e32 v78, v78
	v_exp_f32_e32 v79, v79
	v_exp_f32_e32 v80, v80
	v_exp_f32_e32 v81, v81
	v_exp_f32_e32 v82, v82
	v_exp_f32_e32 v83, v83
	v_exp_f32_e32 v84, v84
	v_exp_f32_e32 v85, v85
	v_exp_f32_e32 v86, v86
	v_exp_f32_e32 v87, v87
	v_exp_f32_e32 v88, v88
	v_exp_f32_e32 v89, v89
	v_exp_f32_e32 v90, v90
	v_exp_f32_e32 v91, v91
	v_exp_f32_e32 v92, v92
	v_exp_f32_e32 v93, v93
	v_exp_f32_e32 v94, v94
	v_exp_f32_e32 v95, v95
	v_pk_add_f32 v[64:65], v[64:65], 1.0 op_sel_hi:[1,0]
	v_pk_add_f32 v[66:67], v[66:67], 1.0 op_sel_hi:[1,0]
	v_pk_add_f32 v[68:69], v[68:69], 1.0 op_sel_hi:[1,0]
	v_pk_add_f32 v[70:71], v[70:71], 1.0 op_sel_hi:[1,0]
	v_pk_add_f32 v[72:73], v[72:73], 1.0 op_sel_hi:[1,0]
	v_pk_add_f32 v[74:75], v[74:75], 1.0 op_sel_hi:[1,0]
	v_pk_add_f32 v[76:77], v[76:77], 1.0 op_sel_hi:[1,0]
	v_pk_add_f32 v[78:79], v[78:79], 1.0 op_sel_hi:[1,0]
	v_pk_add_f32 v[80:81], v[80:81], 1.0 op_sel_hi:[1,0]
	v_pk_add_f32 v[82:83], v[82:83], 1.0 op_sel_hi:[1,0]
	v_pk_add_f32 v[84:85], v[84:85], 1.0 op_sel_hi:[1,0]
	v_pk_add_f32 v[86:87], v[86:87], 1.0 op_sel_hi:[1,0]
	v_pk_add_f32 v[88:89], v[88:89], 1.0 op_sel_hi:[1,0]
	v_pk_add_f32 v[90:91], v[90:91], 1.0 op_sel_hi:[1,0]
	v_pk_add_f32 v[92:93], v[92:93], 1.0 op_sel_hi:[1,0]
	v_pk_add_f32 v[94:95], v[94:95], 1.0 op_sel_hi:[1,0]
	v_rcp_f32_e32 v64, v64
	v_rcp_f32_e32 v65, v65
	v_rcp_f32_e32 v66, v66
	v_rcp_f32_e32 v67, v67
	v_rcp_f32_e32 v68, v68
	v_rcp_f32_e32 v69, v69
	v_rcp_f32_e32 v70, v70
	v_rcp_f32_e32 v71, v71
	v_rcp_f32_e32 v72, v72
	v_rcp_f32_e32 v73, v73
	v_rcp_f32_e32 v74, v74
	v_rcp_f32_e32 v75, v75
	v_rcp_f32_e32 v76, v76
	v_rcp_f32_e32 v77, v77
	v_rcp_f32_e32 v78, v78
	v_rcp_f32_e32 v79, v79
	v_rcp_f32_e32 v80, v80
	v_rcp_f32_e32 v81, v81
	v_rcp_f32_e32 v82, v82
	v_rcp_f32_e32 v83, v83
	v_rcp_f32_e32 v84, v84
	v_rcp_f32_e32 v85, v85
	v_rcp_f32_e32 v86, v86
	v_rcp_f32_e32 v87, v87
	v_rcp_f32_e32 v88, v88
	v_rcp_f32_e32 v89, v89
	v_rcp_f32_e32 v90, v90
	v_rcp_f32_e32 v91, v91
	v_rcp_f32_e32 v92, v92
	v_rcp_f32_e32 v93, v93
	v_rcp_f32_e32 v94, v94
	v_rcp_f32_e32 v95, v95
	s_nop 0
	v_cvt_pk_bf16_f32 v64, v64, v65
	v_cvt_pk_bf16_f32 v65, v66, v67
	v_cvt_pk_bf16_f32 v66, v68, v69
	v_cvt_pk_bf16_f32 v67, v70, v71
	v_cvt_pk_bf16_f32 v68, v72, v73
	v_cvt_pk_bf16_f32 v69, v74, v75
	v_cvt_pk_bf16_f32 v70, v76, v77
	v_cvt_pk_bf16_f32 v71, v78, v79
	v_cvt_pk_bf16_f32 v80, v80, v81
	v_cvt_pk_bf16_f32 v81, v82, v83
	v_cvt_pk_bf16_f32 v82, v84, v85
	v_cvt_pk_bf16_f32 v83, v86, v87
	v_cvt_pk_bf16_f32 v84, v88, v89
	v_cvt_pk_bf16_f32 v85, v90, v91
	v_cvt_pk_bf16_f32 v86, v92, v93
	v_cvt_pk_bf16_f32 v87, v94, v95
	v_permlane32_swap_b32_e32 v64, v66
	v_permlane32_swap_b32_e32 v65, v67
	v_permlane32_swap_b32_e32 v68, v70
	v_permlane32_swap_b32_e32 v69, v71
	v_permlane32_swap_b32_e32 v80, v82
	v_permlane32_swap_b32_e32 v81, v83
	v_permlane32_swap_b32_e32 v84, v86
	v_permlane32_swap_b32_e32 v85, v87
	global_store_dwordx4 v181, v[64:67], s[74:75] offset:0
	global_store_dwordx4 v181, v[68:71], s[74:75] offset:32
	global_store_dwordx4 v181, v[80:83], s[74:75] offset:64
	global_store_dwordx4 v181, v[84:87], s[74:75] offset:96
	s_add_u32 s74, s74, 0x44000
	s_addc_u32 s75, s75, 0
	v_pk_fma_f32 v[96:97], v[96:97], v[174:175], v[198:199] op_sel:[0,1,0] op_sel_hi:[1,1,1]
	v_pk_fma_f32 v[98:99], v[98:99], v[174:175], v[200:201] op_sel:[0,1,0] op_sel_hi:[1,1,1]
	v_pk_fma_f32 v[100:101], v[100:101], v[174:175], v[202:203] op_sel:[0,1,0] op_sel_hi:[1,1,1]
	v_pk_fma_f32 v[102:103], v[102:103], v[174:175], v[204:205] op_sel:[0,1,0] op_sel_hi:[1,1,1]
	v_pk_fma_f32 v[104:105], v[104:105], v[174:175], v[206:207] op_sel:[0,1,0] op_sel_hi:[1,1,1]
	v_pk_fma_f32 v[106:107], v[106:107], v[174:175], v[208:209] op_sel:[0,1,0] op_sel_hi:[1,1,1]
	v_pk_fma_f32 v[108:109], v[108:109], v[174:175], v[210:211] op_sel:[0,1,0] op_sel_hi:[1,1,1]
	v_pk_fma_f32 v[110:111], v[110:111], v[174:175], v[212:213] op_sel:[0,1,0] op_sel_hi:[1,1,1]
	v_pk_fma_f32 v[112:113], v[112:113], v[174:175], v[214:215] op_sel:[0,1,0] op_sel_hi:[1,1,1]
	v_pk_fma_f32 v[114:115], v[114:115], v[174:175], v[216:217] op_sel:[0,1,0] op_sel_hi:[1,1,1]
	v_pk_fma_f32 v[116:117], v[116:117], v[174:175], v[218:219] op_sel:[0,1,0] op_sel_hi:[1,1,1]
	v_pk_fma_f32 v[118:119], v[118:119], v[174:175], v[220:221] op_sel:[0,1,0] op_sel_hi:[1,1,1]
	v_pk_fma_f32 v[120:121], v[120:121], v[174:175], v[222:223] op_sel:[0,1,0] op_sel_hi:[1,1,1]
	v_pk_fma_f32 v[122:123], v[122:123], v[174:175], v[224:225] op_sel:[0,1,0] op_sel_hi:[1,1,1]
	v_pk_fma_f32 v[124:125], v[124:125], v[174:175], v[226:227] op_sel:[0,1,0] op_sel_hi:[1,1,1]
	v_pk_fma_f32 v[126:127], v[126:127], v[174:175], v[228:229] op_sel:[0,1,0] op_sel_hi:[1,1,1]
	v_exp_f32_e32 v96, v96
	v_exp_f32_e32 v97, v97
	v_exp_f32_e32 v98, v98
	v_exp_f32_e32 v99, v99
	v_exp_f32_e32 v100, v100
	v_exp_f32_e32 v101, v101
	v_exp_f32_e32 v102, v102
	v_exp_f32_e32 v103, v103
	v_exp_f32_e32 v104, v104
	v_exp_f32_e32 v105, v105
	v_exp_f32_e32 v106, v106
	v_exp_f32_e32 v107, v107
	v_exp_f32_e32 v108, v108
	v_exp_f32_e32 v109, v109
	v_exp_f32_e32 v110, v110
	v_exp_f32_e32 v111, v111
	v_exp_f32_e32 v112, v112
	v_exp_f32_e32 v113, v113
	v_exp_f32_e32 v114, v114
	v_exp_f32_e32 v115, v115
	v_exp_f32_e32 v116, v116
	v_exp_f32_e32 v117, v117
	v_exp_f32_e32 v118, v118
	v_exp_f32_e32 v119, v119
	v_exp_f32_e32 v120, v120
	v_exp_f32_e32 v121, v121
	v_exp_f32_e32 v122, v122
	v_exp_f32_e32 v123, v123
	v_exp_f32_e32 v124, v124
	v_exp_f32_e32 v125, v125
	v_exp_f32_e32 v126, v126
	v_exp_f32_e32 v127, v127
	v_pk_add_f32 v[96:97], v[96:97], 1.0 op_sel_hi:[1,0]
	v_pk_add_f32 v[98:99], v[98:99], 1.0 op_sel_hi:[1,0]
	v_pk_add_f32 v[100:101], v[100:101], 1.0 op_sel_hi:[1,0]
	v_pk_add_f32 v[102:103], v[102:103], 1.0 op_sel_hi:[1,0]
	v_pk_add_f32 v[104:105], v[104:105], 1.0 op_sel_hi:[1,0]
	v_pk_add_f32 v[106:107], v[106:107], 1.0 op_sel_hi:[1,0]
	v_pk_add_f32 v[108:109], v[108:109], 1.0 op_sel_hi:[1,0]
	v_pk_add_f32 v[110:111], v[110:111], 1.0 op_sel_hi:[1,0]
	v_pk_add_f32 v[112:113], v[112:113], 1.0 op_sel_hi:[1,0]
	v_pk_add_f32 v[114:115], v[114:115], 1.0 op_sel_hi:[1,0]
	v_pk_add_f32 v[116:117], v[116:117], 1.0 op_sel_hi:[1,0]
	v_pk_add_f32 v[118:119], v[118:119], 1.0 op_sel_hi:[1,0]
	v_pk_add_f32 v[120:121], v[120:121], 1.0 op_sel_hi:[1,0]
	v_pk_add_f32 v[122:123], v[122:123], 1.0 op_sel_hi:[1,0]
	v_pk_add_f32 v[124:125], v[124:125], 1.0 op_sel_hi:[1,0]
	v_pk_add_f32 v[126:127], v[126:127], 1.0 op_sel_hi:[1,0]
	v_rcp_f32_e32 v96, v96
	v_rcp_f32_e32 v97, v97
	v_rcp_f32_e32 v98, v98
	v_rcp_f32_e32 v99, v99
	v_rcp_f32_e32 v100, v100
	v_rcp_f32_e32 v101, v101
	v_rcp_f32_e32 v102, v102
	v_rcp_f32_e32 v103, v103
	v_rcp_f32_e32 v104, v104
	v_rcp_f32_e32 v105, v105
	v_rcp_f32_e32 v106, v106
	v_rcp_f32_e32 v107, v107
	v_rcp_f32_e32 v108, v108
	v_rcp_f32_e32 v109, v109
	v_rcp_f32_e32 v110, v110
	v_rcp_f32_e32 v111, v111
	v_rcp_f32_e32 v112, v112
	v_rcp_f32_e32 v113, v113
	v_rcp_f32_e32 v114, v114
	v_rcp_f32_e32 v115, v115
	v_rcp_f32_e32 v116, v116
	v_rcp_f32_e32 v117, v117
	v_rcp_f32_e32 v118, v118
	v_rcp_f32_e32 v119, v119
	v_rcp_f32_e32 v120, v120
	v_rcp_f32_e32 v121, v121
	v_rcp_f32_e32 v122, v122
	v_rcp_f32_e32 v123, v123
	v_rcp_f32_e32 v124, v124
	v_rcp_f32_e32 v125, v125
	v_rcp_f32_e32 v126, v126
	v_rcp_f32_e32 v127, v127
	s_nop 0
	v_cvt_pk_bf16_f32 v96, v96, v97
	v_cvt_pk_bf16_f32 v97, v98, v99
	v_cvt_pk_bf16_f32 v98, v100, v101
	v_cvt_pk_bf16_f32 v99, v102, v103
	v_cvt_pk_bf16_f32 v100, v104, v105
	v_cvt_pk_bf16_f32 v101, v106, v107
	v_cvt_pk_bf16_f32 v102, v108, v109
	v_cvt_pk_bf16_f32 v103, v110, v111
	v_cvt_pk_bf16_f32 v112, v112, v113
	v_cvt_pk_bf16_f32 v113, v114, v115
	v_cvt_pk_bf16_f32 v114, v116, v117
	v_cvt_pk_bf16_f32 v115, v118, v119
	v_cvt_pk_bf16_f32 v116, v120, v121
	v_cvt_pk_bf16_f32 v117, v122, v123
	v_cvt_pk_bf16_f32 v118, v124, v125
	v_cvt_pk_bf16_f32 v119, v126, v127
	v_permlane32_swap_b32_e32 v96, v98
	v_permlane32_swap_b32_e32 v97, v99
	v_permlane32_swap_b32_e32 v100, v102
	v_permlane32_swap_b32_e32 v101, v103
	v_permlane32_swap_b32_e32 v112, v114
	v_permlane32_swap_b32_e32 v113, v115
	v_permlane32_swap_b32_e32 v116, v118
	v_permlane32_swap_b32_e32 v117, v119
	global_store_dwordx4 v181, v[96:99], s[74:75] offset:0
	global_store_dwordx4 v181, v[100:103], s[74:75] offset:32
	global_store_dwordx4 v181, v[112:115], s[74:75] offset:64
	global_store_dwordx4 v181, v[116:119], s[74:75] offset:96
	s_branch .Lpe_ret_L1
.Lpe_vt_L1:
	s_lshl_b32 s35, s34, 2
	s_add_u32 s35, s35, s28
	s_add_u32 s36, s28, 6
	s_cmp_eq_u32 s25, 8
	s_cselect_b32 s35, s36, s35
	s_lshr_b32 s36, s29, 11
	s_mul_i32 s36, s36, 10
	s_add_u32 s36, s36, s35
	s_lshl_b32 s36, s36, 18
	s_and_b32 s37, s29, 0x7ff
	s_lshl_b32 s37, s37, 1
	s_add_u32 s36, s36, s37
	s_add_u32 s38, s72, 0x14920000
	s_addc_u32 s39, s73, 0
	s_add_u32 s38, s38, s36
	s_addc_u32 s39, s39, 0
	s_mul_i32 s36, s26, 10240
	s_add_u32 s36, s36, 0x10000
	v_lshlrev_b32_e32 v180, 1, v197
	v_mul_u32_u24_e32 v181, 36, v146
	v_add3_u32 v180, v180, v181, s36
	v_lshrrev_b32_e32 v181, 3, v179
	v_and_b32_e32 v146, 7, v179
	v_lshlrev_b32_e32 v146, 4, v146
	v_mul_u32_u24_e32 v198, 144, v181
	v_add3_u32 v198, v198, v146, s36
	v_lshl_add_u32 v199, v181, 12, v146
	s_waitcnt vmcnt(0)
	v_mov_b32_e32 v197, 0x358637bd
	v_pk_add_f32 v[128:129], v[128:129], v[130:131]
	v_pk_add_f32 v[132:133], v[132:133], v[134:135]
	v_pk_add_f32 v[136:137], v[136:137], v[138:139]
	v_pk_add_f32 v[140:141], v[140:141], v[142:143]
	v_pk_add_f32 v[164:165], v[164:165], v[166:167]
	v_pk_add_f32 v[168:169], v[168:169], v[170:171]
	v_pk_add_f32 v[246:247], v[246:247], v[248:249]
	v_pk_add_f32 v[250:251], v[250:251], v[252:253]
	v_pk_add_f32 v[128:129], v[128:129], v[132:133]
	v_pk_add_f32 v[136:137], v[136:137], v[140:141]
	v_pk_add_f32 v[164:165], v[164:165], v[168:169]
	v_pk_add_f32 v[246:247], v[246:247], v[250:251]
	v_add_f32_e32 v128, v128, v129
	v_add_f32_e32 v136, v136, v137
	v_add_f32_e32 v164, v164, v165
	v_add_f32_e32 v246, v246, v247
	v_fmamk_f32 v128, v128, 0x3a800000, v197
	v_fmamk_f32 v136, v136, 0x3a800000, v197
	v_fmamk_f32 v164, v164, 0x3a800000, v197
	v_fmamk_f32 v246, v246, 0x3a800000, v197
	v_rsq_f32_e32 v172, v128
	v_rsq_f32_e32 v173, v136
	v_rsq_f32_e32 v174, v164
	v_rsq_f32_e32 v175, v246
	s_nop 0
	s_add_u32 s76, s99, s90
	s_cmp_lt_u32 s76, 0x440
	s_cselect_b32 s80, 1, 0
	s_cselect_b32 s83, 0x200000, 0
	s_lshl_b32 s76, s24, 19
	s_lshl_b32 s77, s26, 16
	s_add_u32 s76, s76, s77
	s_and_b32 s77, s24, 7
	s_lshl_b32 s77, s77, 8
	s_add_u32 s76, s76, s77
	s_add_u32 s78, s72, 0xa120000
	s_addc_u32 s79, s73, 0
	s_add_u32 s78, s78, s76
	s_addc_u32 s79, s79, 0
	s_lshl_b32 s76, s25, 19
	s_add_u32 s76, s76, s83
	s_add_u32 s76, s76, s77
	s_lshl_b32 s77, s26, 16
	s_add_u32 s76, s76, s77
	s_add_u32 s82, s72, 0x880000
	s_addc_u32 s83, s73, 0
	s_add_u32 s82, s82, s76
	s_addc_u32 s83, s83, 0
	s_lshl_b32 s76, s26, 12
	s_mov_b32 m0, s76
	s_nop 0
	global_load_lds_dwordx4 v177, s[78:79]
	s_add_u32 s78, s78, 0x4000
	s_addc_u32 s79, s79, 0
	s_add_u32 s76, s76, 0x400
	s_mov_b32 m0, s76
	s_nop 0
	global_load_lds_dwordx4 v185, s[78:79]
	s_add_u32 s78, s78, 0x4000
	s_addc_u32 s79, s79, 0
	s_add_u32 s76, s76, 0x400
	s_mov_b32 m0, s76
	s_nop 0
	global_load_lds_dwordx4 v177, s[78:79]
	s_add_u32 s78, s78, 0x4000
	s_addc_u32 s79, s79, 0
	s_add_u32 s76, s76, 0x400
	s_mov_b32 m0, s76
	s_nop 0
	global_load_lds_dwordx4 v185, s[78:79]
	s_add_u32 s78, s78, 0x4000
	s_addc_u32 s79, s79, 0
	s_add_u32 s76, s76, 0x400
	s_add_u32 s76, s76, 0x7000
	s_mov_b32 m0, s76
	s_nop 0
	global_load_lds_dwordx4 v177, s[82:83]
	s_add_u32 s82, s82, 0x4000
	s_addc_u32 s83, s83, 0
	s_add_u32 s76, s76, 0x400
	s_mov_b32 m0, s76
	s_nop 0
	global_load_lds_dwordx4 v185, s[82:83]
	s_add_u32 s82, s82, 0x4000
	s_addc_u32 s83, s83, 0
	s_add_u32 s76, s76, 0x400
	s_mov_b32 m0, s76
	s_nop 0
	global_load_lds_dwordx4 v177, s[82:83]
	s_add_u32 s82, s82, 0x4000
	s_addc_u32 s83, s83, 0
	s_add_u32 s76, s76, 0x400
	s_mov_b32 m0, s76
	s_nop 0
	global_load_lds_dwordx4 v185, s[82:83]
	s_add_u32 s82, s82, 0x4000
	s_addc_u32 s83, s83, 0
	s_add_u32 s76, s76, 0x400
	s_and_b32 s77, s24, 7
	s_lshl_b32 s77, s77, 8
	s_add_u32 s76, s77, 0x10000
	s_sub_u32 s78, s78, s76
	s_subb_u32 s79, s79, 0
	s_sub_u32 s82, s82, s76
	s_subb_u32 s83, s83, 0
	s_sub_u32 s76, s78, s82
	v_lshrrev_b32_e32 v196, 5, v179
	v_add_u32_e32 v196, -1, v196
	v_and_b32_e32 v196, s76, v196
	v_and_b32_e32 v194, 31, v179
	v_lshl_add_u32 v194, v194, 11, v196
	s_add_u32 s76, s77, 0x80
	s_and_b32 s76, s76, 0x7ff
	s_add_u32 s78, s82, s76
	s_addc_u32 s79, s83, 0
	global_load_dword v195, v194, s[78:79]
	s_add_u32 s76, s77, 0x100
	s_and_b32 s76, s76, 0x7ff
	s_add_u32 s78, s82, s76
	s_addc_u32 s79, s83, 0
	global_load_dword v195, v194, s[78:79]
	s_add_u32 s76, s77, 0x180
	s_and_b32 s76, s76, 0x7ff
	s_add_u32 s78, s82, s76
	s_addc_u32 s79, s83, 0
	global_load_dword v195, v194, s[78:79]
	s_add_u32 s76, s77, 0x200
	s_and_b32 s76, s76, 0x7ff
	s_add_u32 s78, s82, s76
	s_addc_u32 s79, s83, 0
	global_load_dword v195, v194, s[78:79]
	v_pk_mul_f32 v[0:1], v[0:1], v[172:173] op_sel_hi:[1,0]
	v_pk_mul_f32 v[2:3], v[2:3], v[172:173] op_sel_hi:[1,0]
	v_pk_mul_f32 v[4:5], v[4:5], v[172:173] op_sel_hi:[1,0]
	v_pk_mul_f32 v[6:7], v[6:7], v[172:173] op_sel_hi:[1,0]
	v_pk_mul_f32 v[8:9], v[8:9], v[172:173] op_sel_hi:[1,0]
	v_pk_mul_f32 v[10:11], v[10:11], v[172:173] op_sel_hi:[1,0]
	v_pk_mul_f32 v[12:13], v[12:13], v[172:173] op_sel_hi:[1,0]
	v_pk_mul_f32 v[14:15], v[14:15], v[172:173] op_sel_hi:[1,0]
	v_pk_mul_f32 v[16:17], v[16:17], v[172:173] op_sel_hi:[1,0]
	v_pk_mul_f32 v[18:19], v[18:19], v[172:173] op_sel_hi:[1,0]
	v_pk_mul_f32 v[20:21], v[20:21], v[172:173] op_sel_hi:[1,0]
	v_pk_mul_f32 v[22:23], v[22:23], v[172:173] op_sel_hi:[1,0]
	v_pk_mul_f32 v[24:25], v[24:25], v[172:173] op_sel_hi:[1,0]
	v_pk_mul_f32 v[26:27], v[26:27], v[172:173] op_sel_hi:[1,0]
	v_pk_mul_f32 v[28:29], v[28:29], v[172:173] op_sel_hi:[1,0]
	v_pk_mul_f32 v[30:31], v[30:31], v[172:173] op_sel_hi:[1,0]
	v_pk_mul_f32 v[32:33], v[32:33], v[172:173] op_sel:[0,1] op_sel_hi:[1,1]
	v_pk_mul_f32 v[34:35], v[34:35], v[172:173] op_sel:[0,1] op_sel_hi:[1,1]
	v_pk_mul_f32 v[36:37], v[36:37], v[172:173] op_sel:[0,1] op_sel_hi:[1,1]
	v_pk_mul_f32 v[38:39], v[38:39], v[172:173] op_sel:[0,1] op_sel_hi:[1,1]
	v_pk_mul_f32 v[40:41], v[40:41], v[172:173] op_sel:[0,1] op_sel_hi:[1,1]
	v_pk_mul_f32 v[42:43], v[42:43], v[172:173] op_sel:[0,1] op_sel_hi:[1,1]
	v_pk_mul_f32 v[44:45], v[44:45], v[172:173] op_sel:[0,1] op_sel_hi:[1,1]
	v_pk_mul_f32 v[46:47], v[46:47], v[172:173] op_sel:[0,1] op_sel_hi:[1,1]
	v_pk_mul_f32 v[48:49], v[48:49], v[172:173] op_sel:[0,1] op_sel_hi:[1,1]
	v_pk_mul_f32 v[50:51], v[50:51], v[172:173] op_sel:[0,1] op_sel_hi:[1,1]
	v_pk_mul_f32 v[52:53], v[52:53], v[172:173] op_sel:[0,1] op_sel_hi:[1,1]
	v_pk_mul_f32 v[54:55], v[54:55], v[172:173] op_sel:[0,1] op_sel_hi:[1,1]
	v_pk_mul_f32 v[56:57], v[56:57], v[172:173] op_sel:[0,1] op_sel_hi:[1,1]
	v_pk_mul_f32 v[58:59], v[58:59], v[172:173] op_sel:[0,1] op_sel_hi:[1,1]
	v_pk_mul_f32 v[60:61], v[60:61], v[172:173] op_sel:[0,1] op_sel_hi:[1,1]
	v_pk_mul_f32 v[62:63], v[62:63], v[172:173] op_sel:[0,1] op_sel_hi:[1,1]
	v_pk_mul_f32 v[64:65], v[64:65], v[174:175] op_sel_hi:[1,0]
	v_pk_mul_f32 v[66:67], v[66:67], v[174:175] op_sel_hi:[1,0]
	v_pk_mul_f32 v[68:69], v[68:69], v[174:175] op_sel_hi:[1,0]
	v_pk_mul_f32 v[70:71], v[70:71], v[174:175] op_sel_hi:[1,0]
	v_pk_mul_f32 v[72:73], v[72:73], v[174:175] op_sel_hi:[1,0]
	v_pk_mul_f32 v[74:75], v[74:75], v[174:175] op_sel_hi:[1,0]
	v_pk_mul_f32 v[76:77], v[76:77], v[174:175] op_sel_hi:[1,0]
	v_pk_mul_f32 v[78:79], v[78:79], v[174:175] op_sel_hi:[1,0]
	v_pk_mul_f32 v[80:81], v[80:81], v[174:175] op_sel_hi:[1,0]
	v_pk_mul_f32 v[82:83], v[82:83], v[174:175] op_sel_hi:[1,0]
	v_pk_mul_f32 v[84:85], v[84:85], v[174:175] op_sel_hi:[1,0]
	v_pk_mul_f32 v[86:87], v[86:87], v[174:175] op_sel_hi:[1,0]
	v_pk_mul_f32 v[88:89], v[88:89], v[174:175] op_sel_hi:[1,0]
	v_pk_mul_f32 v[90:91], v[90:91], v[174:175] op_sel_hi:[1,0]
	v_pk_mul_f32 v[92:93], v[92:93], v[174:175] op_sel_hi:[1,0]
	v_pk_mul_f32 v[94:95], v[94:95], v[174:175] op_sel_hi:[1,0]
	v_pk_mul_f32 v[96:97], v[96:97], v[174:175] op_sel:[0,1] op_sel_hi:[1,1]
	v_pk_mul_f32 v[98:99], v[98:99], v[174:175] op_sel:[0,1] op_sel_hi:[1,1]
	v_pk_mul_f32 v[100:101], v[100:101], v[174:175] op_sel:[0,1] op_sel_hi:[1,1]
	v_pk_mul_f32 v[102:103], v[102:103], v[174:175] op_sel:[0,1] op_sel_hi:[1,1]
	v_pk_mul_f32 v[104:105], v[104:105], v[174:175] op_sel:[0,1] op_sel_hi:[1,1]
	v_pk_mul_f32 v[106:107], v[106:107], v[174:175] op_sel:[0,1] op_sel_hi:[1,1]
	v_pk_mul_f32 v[108:109], v[108:109], v[174:175] op_sel:[0,1] op_sel_hi:[1,1]
	v_pk_mul_f32 v[110:111], v[110:111], v[174:175] op_sel:[0,1] op_sel_hi:[1,1]
	v_pk_mul_f32 v[112:113], v[112:113], v[174:175] op_sel:[0,1] op_sel_hi:[1,1]
	v_pk_mul_f32 v[114:115], v[114:115], v[174:175] op_sel:[0,1] op_sel_hi:[1,1]
	v_pk_mul_f32 v[116:117], v[116:117], v[174:175] op_sel:[0,1] op_sel_hi:[1,1]
	v_pk_mul_f32 v[118:119], v[118:119], v[174:175] op_sel:[0,1] op_sel_hi:[1,1]
	v_pk_mul_f32 v[120:121], v[120:121], v[174:175] op_sel:[0,1] op_sel_hi:[1,1]
	v_pk_mul_f32 v[122:123], v[122:123], v[174:175] op_sel:[0,1] op_sel_hi:[1,1]
	v_pk_mul_f32 v[124:125], v[124:125], v[174:175] op_sel:[0,1] op_sel_hi:[1,1]
	v_pk_mul_f32 v[126:127], v[126:127], v[174:175] op_sel:[0,1] op_sel_hi:[1,1]
	v_cvt_pk_bf16_f32 v0, v0, v1
	v_cvt_pk_bf16_f32 v1, v2, v3
	v_cvt_pk_bf16_f32 v2, v4, v5
	v_cvt_pk_bf16_f32 v3, v6, v7
	v_cvt_pk_bf16_f32 v4, v8, v9
	v_cvt_pk_bf16_f32 v5, v10, v11
	v_cvt_pk_bf16_f32 v6, v12, v13
	v_cvt_pk_bf16_f32 v7, v14, v15
	ds_write_b16 v180, v0 offset:0
	ds_write_b16_d16_hi v180, v0 offset:144
	ds_write_b16 v180, v1 offset:288
	ds_write_b16_d16_hi v180, v1 offset:432
	ds_write_b16 v180, v2 offset:1152
	ds_write_b16_d16_hi v180, v2 offset:1296
	ds_write_b16 v180, v3 offset:1440
	ds_write_b16_d16_hi v180, v3 offset:1584
	ds_write_b16 v180, v4 offset:2304
	ds_write_b16_d16_hi v180, v4 offset:2448
	ds_write_b16 v180, v5 offset:2592
	ds_write_b16_d16_hi v180, v5 offset:2736
	ds_write_b16 v180, v6 offset:3456
	ds_write_b16_d16_hi v180, v6 offset:3600
	ds_write_b16 v180, v7 offset:3744
	ds_write_b16_d16_hi v180, v7 offset:3888
	v_cvt_pk_bf16_f32 v16, v16, v17
	v_cvt_pk_bf16_f32 v17, v18, v19
	v_cvt_pk_bf16_f32 v18, v20, v21
	v_cvt_pk_bf16_f32 v19, v22, v23
	v_cvt_pk_bf16_f32 v20, v24, v25
	v_cvt_pk_bf16_f32 v21, v26, v27
	v_cvt_pk_bf16_f32 v22, v28, v29
	v_cvt_pk_bf16_f32 v23, v30, v31
	ds_write_b16 v180, v16 offset:4608
	ds_write_b16_d16_hi v180, v16 offset:4752
	ds_write_b16 v180, v17 offset:4896
	ds_write_b16_d16_hi v180, v17 offset:5040
	ds_write_b16 v180, v18 offset:5760
	ds_write_b16_d16_hi v180, v18 offset:5904
	ds_write_b16 v180, v19 offset:6048
	ds_write_b16_d16_hi v180, v19 offset:6192
	ds_write_b16 v180, v20 offset:6912
	ds_write_b16_d16_hi v180, v20 offset:7056
	ds_write_b16 v180, v21 offset:7200
	ds_write_b16_d16_hi v180, v21 offset:7344
	ds_write_b16 v180, v22 offset:8064
	ds_write_b16_d16_hi v180, v22 offset:8208
	ds_write_b16 v180, v23 offset:8352
	ds_write_b16_d16_hi v180, v23 offset:8496
	v_cvt_pk_bf16_f32 v32, v32, v33
	v_cvt_pk_bf16_f32 v33, v34, v35
	v_cvt_pk_bf16_f32 v34, v36, v37
	v_cvt_pk_bf16_f32 v35, v38, v39
	v_cvt_pk_bf16_f32 v36, v40, v41
	v_cvt_pk_bf16_f32 v37, v42, v43
	v_cvt_pk_bf16_f32 v38, v44, v45
	v_cvt_pk_bf16_f32 v39, v46, v47
	ds_write_b16 v180, v32 offset:64
	ds_write_b16_d16_hi v180, v32 offset:208
	ds_write_b16 v180, v33 offset:352
	ds_write_b16_d16_hi v180, v33 offset:496
	ds_write_b16 v180, v34 offset:1216
	ds_write_b16_d16_hi v180, v34 offset:1360
	ds_write_b16 v180, v35 offset:1504
	ds_write_b16_d16_hi v180, v35 offset:1648
	ds_write_b16 v180, v36 offset:2368
	ds_write_b16_d16_hi v180, v36 offset:2512
	ds_write_b16 v180, v37 offset:2656
	ds_write_b16_d16_hi v180, v37 offset:2800
	ds_write_b16 v180, v38 offset:3520
	ds_write_b16_d16_hi v180, v38 offset:3664
	ds_write_b16 v180, v39 offset:3808
	ds_write_b16_d16_hi v180, v39 offset:3952
	v_cvt_pk_bf16_f32 v48, v48, v49
	v_cvt_pk_bf16_f32 v49, v50, v51
	v_cvt_pk_bf16_f32 v50, v52, v53
	v_cvt_pk_bf16_f32 v51, v54, v55
	v_cvt_pk_bf16_f32 v52, v56, v57
	v_cvt_pk_bf16_f32 v53, v58, v59
	v_cvt_pk_bf16_f32 v54, v60, v61
	v_cvt_pk_bf16_f32 v55, v62, v63
	ds_write_b16 v180, v48 offset:4672
	ds_write_b16_d16_hi v180, v48 offset:4816
	ds_write_b16 v180, v49 offset:4960
	ds_write_b16_d16_hi v180, v49 offset:5104
	ds_write_b16 v180, v50 offset:5824
	ds_write_b16_d16_hi v180, v50 offset:5968
	ds_write_b16 v180, v51 offset:6112
	ds_write_b16_d16_hi v180, v51 offset:6256
	ds_write_b16 v180, v52 offset:6976
	ds_write_b16_d16_hi v180, v52 offset:7120
	ds_write_b16 v180, v53 offset:7264
	ds_write_b16_d16_hi v180, v53 offset:7408
	ds_write_b16 v180, v54 offset:8128
	ds_write_b16_d16_hi v180, v54 offset:8272
	ds_write_b16 v180, v55 offset:8416
	ds_write_b16_d16_hi v180, v55 offset:8560
	s_waitcnt lgkmcnt(0)
	ds_read_b128 v[0:3], v198 offset:0
	ds_read_b128 v[4:7], v198 offset:1152
	ds_read_b128 v[8:11], v198 offset:2304
	ds_read_b128 v[12:15], v198 offset:3456
	ds_read_b128 v[16:19], v198 offset:4608
	ds_read_b128 v[20:23], v198 offset:5760
	ds_read_b128 v[24:27], v198 offset:6912
	ds_read_b128 v[28:31], v198 offset:8064
	s_waitcnt lgkmcnt(7)
	global_store_dwordx4 v199, v[0:3], s[38:39]
	s_add_u32 s38, s38, 0x8000
	s_addc_u32 s39, s39, 0
	s_waitcnt lgkmcnt(6)
	global_store_dwordx4 v199, v[4:7], s[38:39]
	s_add_u32 s38, s38, 0x8000
	s_addc_u32 s39, s39, 0
	s_waitcnt lgkmcnt(5)
	global_store_dwordx4 v199, v[8:11], s[38:39]
	s_add_u32 s38, s38, 0x8000
	s_addc_u32 s39, s39, 0
	s_waitcnt lgkmcnt(4)
	global_store_dwordx4 v199, v[12:15], s[38:39]
	s_add_u32 s38, s38, 0x8000
	s_addc_u32 s39, s39, 0
	s_waitcnt lgkmcnt(3)
	global_store_dwordx4 v199, v[16:19], s[38:39]
	s_add_u32 s38, s38, 0x8000
	s_addc_u32 s39, s39, 0
	s_waitcnt lgkmcnt(2)
	global_store_dwordx4 v199, v[20:23], s[38:39]
	s_add_u32 s38, s38, 0x8000
	s_addc_u32 s39, s39, 0
	s_waitcnt lgkmcnt(1)
	global_store_dwordx4 v199, v[24:27], s[38:39]
	s_add_u32 s38, s38, 0x8000
	s_addc_u32 s39, s39, 0
	s_waitcnt lgkmcnt(0)
	global_store_dwordx4 v199, v[28:31], s[38:39]
	s_sub_u32 s38, s38, 229248
	s_subb_u32 s39, s39, 0
	v_cvt_pk_bf16_f32 v64, v64, v65
	v_cvt_pk_bf16_f32 v65, v66, v67
	v_cvt_pk_bf16_f32 v66, v68, v69
	v_cvt_pk_bf16_f32 v67, v70, v71
	v_cvt_pk_bf16_f32 v68, v72, v73
	v_cvt_pk_bf16_f32 v69, v74, v75
	v_cvt_pk_bf16_f32 v70, v76, v77
	v_cvt_pk_bf16_f32 v71, v78, v79
	ds_write_b16 v180, v64 offset:0
	ds_write_b16_d16_hi v180, v64 offset:144
	ds_write_b16 v180, v65 offset:288
	ds_write_b16_d16_hi v180, v65 offset:432
	ds_write_b16 v180, v66 offset:1152
	ds_write_b16_d16_hi v180, v66 offset:1296
	ds_write_b16 v180, v67 offset:1440
	ds_write_b16_d16_hi v180, v67 offset:1584
	ds_write_b16 v180, v68 offset:2304
	ds_write_b16_d16_hi v180, v68 offset:2448
	ds_write_b16 v180, v69 offset:2592
	ds_write_b16_d16_hi v180, v69 offset:2736
	ds_write_b16 v180, v70 offset:3456
	ds_write_b16_d16_hi v180, v70 offset:3600
	ds_write_b16 v180, v71 offset:3744
	ds_write_b16_d16_hi v180, v71 offset:3888
	v_cvt_pk_bf16_f32 v80, v80, v81
	v_cvt_pk_bf16_f32 v81, v82, v83
	v_cvt_pk_bf16_f32 v82, v84, v85
	v_cvt_pk_bf16_f32 v83, v86, v87
	v_cvt_pk_bf16_f32 v84, v88, v89
	v_cvt_pk_bf16_f32 v85, v90, v91
	v_cvt_pk_bf16_f32 v86, v92, v93
	v_cvt_pk_bf16_f32 v87, v94, v95
	ds_write_b16 v180, v80 offset:4608
	ds_write_b16_d16_hi v180, v80 offset:4752
	ds_write_b16 v180, v81 offset:4896
	ds_write_b16_d16_hi v180, v81 offset:5040
	ds_write_b16 v180, v82 offset:5760
	ds_write_b16_d16_hi v180, v82 offset:5904
	ds_write_b16 v180, v83 offset:6048
	ds_write_b16_d16_hi v180, v83 offset:6192
	ds_write_b16 v180, v84 offset:6912
	ds_write_b16_d16_hi v180, v84 offset:7056
	ds_write_b16 v180, v85 offset:7200
	ds_write_b16_d16_hi v180, v85 offset:7344
	ds_write_b16 v180, v86 offset:8064
	ds_write_b16_d16_hi v180, v86 offset:8208
	ds_write_b16 v180, v87 offset:8352
	ds_write_b16_d16_hi v180, v87 offset:8496
	v_cvt_pk_bf16_f32 v96, v96, v97
	v_cvt_pk_bf16_f32 v97, v98, v99
	v_cvt_pk_bf16_f32 v98, v100, v101
	v_cvt_pk_bf16_f32 v99, v102, v103
	v_cvt_pk_bf16_f32 v100, v104, v105
	v_cvt_pk_bf16_f32 v101, v106, v107
	v_cvt_pk_bf16_f32 v102, v108, v109
	v_cvt_pk_bf16_f32 v103, v110, v111
	ds_write_b16 v180, v96 offset:64
	ds_write_b16_d16_hi v180, v96 offset:208
	ds_write_b16 v180, v97 offset:352
	ds_write_b16_d16_hi v180, v97 offset:496
	ds_write_b16 v180, v98 offset:1216
	ds_write_b16_d16_hi v180, v98 offset:1360
	ds_write_b16 v180, v99 offset:1504
	ds_write_b16_d16_hi v180, v99 offset:1648
	ds_write_b16 v180, v100 offset:2368
	ds_write_b16_d16_hi v180, v100 offset:2512
	ds_write_b16 v180, v101 offset:2656
	ds_write_b16_d16_hi v180, v101 offset:2800
	ds_write_b16 v180, v102 offset:3520
	ds_write_b16_d16_hi v180, v102 offset:3664
	ds_write_b16 v180, v103 offset:3808
	ds_write_b16_d16_hi v180, v103 offset:3952
	v_cvt_pk_bf16_f32 v112, v112, v113
	v_cvt_pk_bf16_f32 v113, v114, v115
	v_cvt_pk_bf16_f32 v114, v116, v117
	v_cvt_pk_bf16_f32 v115, v118, v119
	v_cvt_pk_bf16_f32 v116, v120, v121
	v_cvt_pk_bf16_f32 v117, v122, v123
	v_cvt_pk_bf16_f32 v118, v124, v125
	v_cvt_pk_bf16_f32 v119, v126, v127
	ds_write_b16 v180, v112 offset:4672
	ds_write_b16_d16_hi v180, v112 offset:4816
	ds_write_b16 v180, v113 offset:4960
	ds_write_b16_d16_hi v180, v113 offset:5104
	ds_write_b16 v180, v114 offset:5824
	ds_write_b16_d16_hi v180, v114 offset:5968
	ds_write_b16 v180, v115 offset:6112
	ds_write_b16_d16_hi v180, v115 offset:6256
	ds_write_b16 v180, v116 offset:6976
	ds_write_b16_d16_hi v180, v116 offset:7120
	ds_write_b16 v180, v117 offset:7264
	ds_write_b16_d16_hi v180, v117 offset:7408
	ds_write_b16 v180, v118 offset:8128
	ds_write_b16_d16_hi v180, v118 offset:8272
	ds_write_b16 v180, v119 offset:8416
	ds_write_b16_d16_hi v180, v119 offset:8560
	s_waitcnt lgkmcnt(0)
	ds_read_b128 v[64:67], v198 offset:0
	ds_read_b128 v[68:71], v198 offset:1152
	ds_read_b128 v[72:75], v198 offset:2304
	ds_read_b128 v[76:79], v198 offset:3456
	ds_read_b128 v[80:83], v198 offset:4608
	ds_read_b128 v[84:87], v198 offset:5760
	ds_read_b128 v[88:91], v198 offset:6912
	ds_read_b128 v[92:95], v198 offset:8064
	s_waitcnt lgkmcnt(7)
	global_store_dwordx4 v199, v[64:67], s[38:39]
	s_add_u32 s38, s38, 0x8000
	s_addc_u32 s39, s39, 0
	s_waitcnt lgkmcnt(6)
	global_store_dwordx4 v199, v[68:71], s[38:39]
	s_add_u32 s38, s38, 0x8000
	s_addc_u32 s39, s39, 0
	s_waitcnt lgkmcnt(5)
	global_store_dwordx4 v199, v[72:75], s[38:39]
	s_add_u32 s38, s38, 0x8000
	s_addc_u32 s39, s39, 0
	s_waitcnt lgkmcnt(4)
	global_store_dwordx4 v199, v[76:79], s[38:39]
	s_add_u32 s38, s38, 0x8000
	s_addc_u32 s39, s39, 0
	s_waitcnt lgkmcnt(3)
	global_store_dwordx4 v199, v[80:83], s[38:39]
	s_add_u32 s38, s38, 0x8000
	s_addc_u32 s39, s39, 0
	s_waitcnt lgkmcnt(2)
	global_store_dwordx4 v199, v[84:87], s[38:39]
	s_add_u32 s38, s38, 0x8000
	s_addc_u32 s39, s39, 0
	s_waitcnt lgkmcnt(1)
	global_store_dwordx4 v199, v[88:91], s[38:39]
	s_add_u32 s38, s38, 0x8000
	s_addc_u32 s39, s39, 0
	s_waitcnt lgkmcnt(0)
	global_store_dwordx4 v199, v[92:95], s[38:39]
